# attention: one static s_setprio 1 for waves 4-7 per unit pair, all per-segment priority flips removed (kept as s_nop 0)
# speedup vs baseline: 1.0012x; 1.0012x over previous
; #define LAS __attribute__((address_space(3)))
; __device__ __forceinline__ int otid() { int t = threadIdx.x; asm volatile("" : "+v"(t)); return t; }
; __device__ __forceinline__ void attn_unit(int bh, int qb, const bf16_t* QKV, const bf16_t* KF, const float* cstab, const float* qg, bf16_t* MIX, LAS unsigned char* lds) {
;     const int tid = otid(), lane = tid & 63, r32 = lane & 31, hi = lane >> 5, wid = __builtin_amdgcn_readfirstlane(tid >> 6);
;     const int b = bh >> 3, h = bh & 7, q0 = qb * 256, qw = q0 + 32 * wid, q = qw + r32;
;     bf16x8 qf[6];
;     {
;         const bf16_t* Qp = QKV + (size_t)(b * SEQ + q) * 1792 + h * 96 + 8 * hi;
;         const float* cs = cstab + (size_t)(b * SEQ + q) * 32 + 8 * hi;
;         u32x4 raw[6];
; #pragma unroll
;         for (int d0 = 0; d0 < 6; ++d0) raw[d0] = *(const u32x4*)(Qp + 16 * d0);
;         float ss = 0.f;
; #pragma unroll
;         for (int d0 = 0; d0 < 6; ++d0) { float v[8]; unpack8(raw[d0], v);
; #pragma unroll
;             for (int i = 0; i < 8; ++i) ss += v[i] * v[i]; }
.LBB0_1037:
	v_mov_b32_e32 v143, v228
	s_and_b32 s29, s27, 7
	s_xor_b32 s23, s29, 15
	v_readfirstlane_b32 s2, v143
	s_ashr_i32 s39, s2, 6
	s_cmp_ge_u32 s39, 4
	s_cbranch_scc0 .Lprio_skip_att
	s_setprio 1
.Lprio_skip_att:
	s_lshl_b32 s22, s23, 8
	s_lshl_b32 s37, s39, 5
	s_ashr_i32 s4, s27, 3
	v_and_b32_e32 v138, 31, v143
	s_ashr_i32 s2, s27, 6
	s_add_i32 s37, s37, s22
	s_and_b32 s36, s4, 7
	v_or_b32_e32 v139, s37, v138
	s_lshl_b32 s28, s2, 12
	s_waitcnt vmcnt(5)
	v_add_u32_e32 v24, s28, v139
	v_mov_b64_e32 v[0:1], s[80:81]
	s_mul_i32 s5, s36, 0x60
	v_bfe_u32 v144, v143, 5, 1
	v_mad_i64_i32 v[0:1], s[6:7], v24, s85, v[0:1]
	s_lshl_b32 s78, s5, 1
	v_lshl_add_u64 v[0:1], v[0:1], 0, s[78:79]
	v_lshlrev_b32_e32 v102, 4, v144
	v_mov_b32_e32 v103, v65
	v_lshl_add_u64 v[0:1], v[0:1], 0, v[102:103]
	global_load_dwordx4 v[56:59], v[0:1], off offset:128
	global_load_dwordx4 v[60:63], v[0:1], off offset:160
	global_load_dwordx4 v[66:69], v[0:1], off offset:96
	global_load_dwordx4 v[70:73], v[0:1], off offset:64
	global_load_dwordx4 v[74:77], v[0:1], off offset:32
	global_load_dwordx4 v[108:111], v[0:1], off
	v_and_b32_e32 v64, 32, v143
	global_load_dwordx4 v[0:3], v64, s[0:1] offset:272
	global_load_dwordx4 v[12:15], v64, s[0:1] offset:256
	global_load_dwordx4 v[4:7], v64, s[0:1] offset:336
	global_load_dwordx4 v[8:11], v64, s[0:1] offset:320
	global_load_dwordx4 v[16:19], v64, s[0:1] offset:208
	global_load_dwordx4 v[20:23], v64, s[0:1] offset:192
	global_load_dwordx4 v[40:43], v64, s[0:1] offset:144
	global_load_dwordx4 v[44:47], v64, s[0:1] offset:128
	global_load_dwordx4 v[48:51], v64, s[0:1] offset:80
	global_load_dwordx4 v[52:55], v64, s[0:1] offset:64
	v_ashrrev_i32_e32 v25, 31, v24
	v_lshlrev_b64 v[24:25], 7, v[24:25]
	v_lshl_add_u64 v[24:25], s[8:9], 0, v[24:25]
	s_mul_i32 s31, s4, 0xc0000
	v_lshl_add_u64 v[36:37], v[24:25], 0, v[64:65]
	s_mul_hi_i32 s30, s4, 0xc0000
	s_add_u32 s14, s10, s31
	global_load_dwordx4 v[24:27], v[36:37], off offset:16
	global_load_dwordx4 v[32:35], v[36:37], off
	global_load_dwordx4 v[28:31], v[36:37], off offset:80
	s_nop 0
	global_load_dwordx4 v[36:39], v[36:37], off offset:64
	s_addc_u32 s15, s11, s30
	s_movk_i32 s4, 0x100
	v_cmp_gt_i32_e64 s[6:7], s4, v143
	s_waitcnt vmcnt(19)
	v_lshlrev_b32_e32 v96, 16, v59
	v_and_b32_e32 v97, 0xffff0000, v59
	s_waitcnt vmcnt(17)
	v_lshlrev_b32_e32 v90, 16, v69
	v_and_b32_e32 v91, 0xffff0000, v69
	v_lshlrev_b32_e32 v92, 16, v68
	s_waitcnt vmcnt(14)
; __device__ __forceinline__ float sum32(float v) { const auto rr = __builtin_amdgcn_permlane32_swap(__float_as_uint(v), __float_as_uint(v), false, false); return __uint_as_float(rr[0]) + __uint_as_float(rr[1]); }
; __device__ __forceinline__ u32x4 pack8(const float* v) { u32x4 w; w.x = cvt_pk_bf16(v[0], v[1]); w.y = cvt_pk_bf16(v[2], v[3]); w.z = cvt_pk_bf16(v[4], v[5]); w.w = cvt_pk_bf16(v[6], v[7]); return w; }
; __device__ __forceinline__ void attn_unit(int bh, int qb, const bf16_t* QKV, const bf16_t* KF, const float* cstab, const float* qg, bf16_t* MIX, LAS unsigned char* lds) {
;     ...
;         for (int d0 = 0; d0 < 6; ++d0) raw[d0] = *(const u32x4*)(Qp + 16 * d0);
;         float ss = 0.f;
; #pragma unroll
;         for (int d0 = 0; d0 < 6; ++d0) { float v[8]; unpack8(raw[d0], v);
; #pragma unroll
;             for (int i = 0; i < 8; ++i) ss += v[i] * v[i]; }
;         ss = pg8::sum32(ss);
;         const float rs = __builtin_amdgcn_rsqf(ss * (1.0f / 96.0f) + EPS) * C2Q;
; #pragma unroll
;         for (int d0 = 0; d0 < 4; ++d0) { float v[8]; unpack8(raw[d0], v);
; #pragma unroll
;             for (int i = 0; i < 8; ++i) v[i] = v[i] * rs * qg[16 * d0 + 8 * hi + i];
;             qf[d0] = __builtin_bit_cast(bf16x8, pack8(v)); }
;         float x1[8], x2[8], o1[8], o2[8]; unpack8(raw[4], x1); unpack8(raw[5], x2);
; #pragma unroll
;         for (int i = 0; i < 8; ++i) { const float y1 = x1[i] * rs * qg[64 + 8 * hi + i], y2 = x2[i] * rs * qg[80 + 8 * hi + i], co = cs[i], si = cs[16 + i];
;             o1[i] = y1 * co - y2 * si; o2[i] = y1 * si + y2 * co; }
;         qf[4] = __builtin_bit_cast(bf16x8, pack8(o1)); qf[5] = __builtin_bit_cast(bf16x8, pack8(o2));
;     }
;     const char* Kg = (const char*)(KF + (size_t)bh * SEQ * 96);
;     const char* Vg = (const char*)(QKV + (size_t)b * SEQ * 1792 + 768 + h * 128 + 64) + (size_t)(tid >> 3) * 3584 + (tid & 7) * 16;
;     const int kofs0 = (tid / 12) * KROW + (tid % 12) * 16, kofs1 = ((tid + 512) / 12) * KROW + ((tid + 512) % 12) * 16, vofs = KBUF + (tid >> 3) * VROW + (tid & 7) * 16;
;     const int vtb = KBUF + (4 * hi + ((lane & 15) >> 2)) * VROW + (16 * ((lane >> 4) & 1) + 4 * (lane & 3)) * 2;
;     const int NT = 4 * (qb + 1);
;     u32x4 kr0, kr1 = {0u, 0u, 0u, 0u}, vr;
	v_lshlrev_b32_e32 v132, 16, v108
	v_and_b32_e32 v133, 0xffff0000, v108
	v_lshlrev_b32_e32 v108, 4, v143
	v_lshlrev_b32_e32 v130, 16, v109
	v_and_b32_e32 v131, 0xffff0000, v109
	v_ashrrev_i32_e32 v109, 31, v108
	v_and_b32_e32 v93, 0xffff0000, v68
	v_lshl_add_u64 v[68:69], s[14:15], 0, v[108:109]
	v_lshlrev_b32_e32 v94, 16, v63
	v_and_b32_e32 v95, 0xffff0000, v63
	v_lshlrev_b32_e32 v100, 16, v58
	v_and_b32_e32 v101, 0xffff0000, v58
	v_lshlrev_b32_e32 v98, 16, v62
	v_and_b32_e32 v99, 0xffff0000, v62
	v_lshlrev_b32_e32 v112, 16, v57
	v_and_b32_e32 v113, 0xffff0000, v57
	v_lshlrev_b32_e32 v106, 16, v61
	v_and_b32_e32 v107, 0xffff0000, v61
	v_lshlrev_b32_e32 v116, 16, v56
	v_and_b32_e32 v117, 0xffff0000, v56
	v_lshlrev_b32_e32 v114, 16, v60
	v_and_b32_e32 v115, 0xffff0000, v60
	v_lshlrev_b32_e32 v82, 16, v73
	v_and_b32_e32 v83, 0xffff0000, v73
	v_lshlrev_b32_e32 v84, 16, v72
	v_and_b32_e32 v85, 0xffff0000, v72
	v_lshlrev_b32_e32 v122, 16, v71
	v_and_b32_e32 v123, 0xffff0000, v71
	v_lshlrev_b32_e32 v124, 16, v70
	v_and_b32_e32 v125, 0xffff0000, v70
	global_load_dwordx4 v[56:59], v64, s[0:1] offset:16
	global_load_dwordx4 v[60:63], v64, s[0:1]
	global_load_dwordx4 v[70:73], v[68:69], off
	v_mul_f32_e32 v64, v133, v133
	v_lshlrev_b32_e32 v118, 16, v67
	v_and_b32_e32 v119, 0xffff0000, v67
	v_lshlrev_b32_e32 v120, 16, v66
	v_and_b32_e32 v121, 0xffff0000, v66
	v_pk_fma_f32 v[66:67], v[132:133], v[132:133], v[64:65] op_sel_hi:[1,1,0]
	v_mul_f32_e32 v64, v131, v131
	v_pk_fma_f32 v[66:67], v[130:131], v[130:131], v[66:67]
	v_lshlrev_b32_e32 v128, 16, v110
	v_and_b32_e32 v129, 0xffff0000, v110
	v_pk_add_f32 v[66:67], v[64:65], v[66:67] op_sel_hi:[0,1]
	v_pk_fma_f32 v[66:67], v[128:129], v[128:129], v[66:67]
	v_mul_f32_e32 v64, v129, v129
	v_lshlrev_b32_e32 v126, 16, v111
	v_and_b32_e32 v127, 0xffff0000, v111
	v_pk_add_f32 v[66:67], v[64:65], v[66:67] op_sel_hi:[0,1]
	v_pk_fma_f32 v[66:67], v[126:127], v[126:127], v[66:67]
	v_mul_f32_e32 v64, v127, v127
	v_lshlrev_b32_e32 v88, 16, v74
	v_and_b32_e32 v89, 0xffff0000, v74
	v_pk_add_f32 v[66:67], v[64:65], v[66:67] op_sel_hi:[0,1]
	v_pk_fma_f32 v[66:67], v[88:89], v[88:89], v[66:67]
	v_mul_f32_e32 v64, v89, v89
	v_lshlrev_b32_e32 v86, 16, v75
	v_and_b32_e32 v87, 0xffff0000, v75
	v_pk_add_f32 v[66:67], v[64:65], v[66:67] op_sel_hi:[0,1]
	v_pk_fma_f32 v[66:67], v[86:87], v[86:87], v[66:67]
	v_mul_f32_e32 v64, v87, v87
	v_lshlrev_b32_e32 v80, 16, v76
	v_and_b32_e32 v81, 0xffff0000, v76
	v_pk_add_f32 v[66:67], v[64:65], v[66:67] op_sel_hi:[0,1]
	v_pk_fma_f32 v[66:67], v[80:81], v[80:81], v[66:67]
	v_mul_f32_e32 v64, v81, v81
	v_lshlrev_b32_e32 v78, 16, v77
	v_and_b32_e32 v79, 0xffff0000, v77
	v_pk_add_f32 v[66:67], v[64:65], v[66:67] op_sel_hi:[0,1]
	v_pk_fma_f32 v[66:67], v[78:79], v[78:79], v[66:67]
	v_mul_f32_e32 v64, v79, v79
	v_pk_add_f32 v[66:67], v[64:65], v[66:67] op_sel_hi:[0,1]
	v_pk_fma_f32 v[66:67], v[124:125], v[124:125], v[66:67]
	v_mul_f32_e32 v64, v125, v125
	v_pk_add_f32 v[66:67], v[64:65], v[66:67] op_sel_hi:[0,1]
	v_pk_fma_f32 v[66:67], v[122:123], v[122:123], v[66:67]
	v_mul_f32_e32 v64, v123, v123
	v_pk_add_f32 v[66:67], v[64:65], v[66:67] op_sel_hi:[0,1]
	v_pk_fma_f32 v[66:67], v[84:85], v[84:85], v[66:67]
	v_mul_f32_e32 v64, v85, v85
	v_pk_add_f32 v[66:67], v[64:65], v[66:67] op_sel_hi:[0,1]
	v_pk_fma_f32 v[66:67], v[82:83], v[82:83], v[66:67]
	v_mul_f32_e32 v64, v83, v83
	v_pk_add_f32 v[66:67], v[64:65], v[66:67] op_sel_hi:[0,1]
	v_pk_fma_f32 v[66:67], v[120:121], v[120:121], v[66:67]
	v_mul_f32_e32 v64, v121, v121
	v_pk_add_f32 v[66:67], v[64:65], v[66:67] op_sel_hi:[0,1]
	v_pk_fma_f32 v[66:67], v[118:119], v[118:119], v[66:67]
	v_mul_f32_e32 v64, v119, v119
	v_pk_add_f32 v[66:67], v[64:65], v[66:67] op_sel_hi:[0,1]
	v_pk_fma_f32 v[66:67], v[92:93], v[92:93], v[66:67]
	v_mul_f32_e32 v64, v93, v93
	v_pk_add_f32 v[66:67], v[64:65], v[66:67] op_sel_hi:[0,1]
	v_pk_fma_f32 v[66:67], v[90:91], v[90:91], v[66:67]
	v_mul_f32_e32 v64, v91, v91
	v_pk_add_f32 v[66:67], v[64:65], v[66:67] op_sel_hi:[0,1]
	v_pk_fma_f32 v[66:67], v[116:117], v[116:117], v[66:67]
	v_mul_f32_e32 v64, v117, v117
	v_pk_add_f32 v[66:67], v[64:65], v[66:67] op_sel_hi:[0,1]
	v_pk_fma_f32 v[66:67], v[112:113], v[112:113], v[66:67]
	v_mul_f32_e32 v64, v113, v113
	v_pk_add_f32 v[66:67], v[64:65], v[66:67] op_sel_hi:[0,1]
	v_pk_fma_f32 v[66:67], v[100:101], v[100:101], v[66:67]
	v_mul_f32_e32 v64, v101, v101
	v_pk_add_f32 v[66:67], v[64:65], v[66:67] op_sel_hi:[0,1]
	v_pk_fma_f32 v[66:67], v[96:97], v[96:97], v[66:67]
	v_mul_f32_e32 v64, v97, v97
	v_pk_add_f32 v[66:67], v[64:65], v[66:67] op_sel_hi:[0,1]
	v_pk_fma_f32 v[66:67], v[114:115], v[114:115], v[66:67]
	v_mul_f32_e32 v64, v115, v115
	v_pk_add_f32 v[66:67], v[64:65], v[66:67] op_sel_hi:[0,1]
	v_pk_fma_f32 v[66:67], v[106:107], v[106:107], v[66:67]
	v_mul_f32_e32 v64, v107, v107
	v_pk_add_f32 v[66:67], v[64:65], v[66:67] op_sel_hi:[0,1]
	v_pk_fma_f32 v[66:67], v[98:99], v[98:99], v[66:67]
	v_mul_f32_e32 v64, v99, v99
	v_pk_add_f32 v[66:67], v[64:65], v[66:67] op_sel_hi:[0,1]
	v_pk_fma_f32 v[66:67], v[94:95], v[94:95], v[66:67]
	v_mul_f32_e32 v64, v95, v95
	v_pk_add_f32 v[134:135], v[64:65], v[66:67] op_sel_hi:[0,1]
	v_add_u32_e32 v74, 0x200, v143
	v_mov_b32_e32 v66, v65
	v_mov_b32_e32 v67, v65
	v_mov_b32_e32 v146, v134
	v_mov_b32_e32 v64, v65
	v_lshlrev_b32_e32 v110, 4, v74
	v_mov_b64_e32 v[68:69], v[66:67]
	v_permlane32_swap_b32_e32 v134, v146
	v_ashrrev_i32_e32 v111, 31, v110
	v_mov_b64_e32 v[66:67], v[64:65]
	s_and_saveexec_b64 s[4:5], s[6:7]
	s_cbranch_execz .LBB0_1039
	v_lshl_add_u64 v[66:67], s[14:15], 0, v[110:111]
	global_load_dwordx4 v[66:69], v[66:67], off

; #define LAS __attribute__((address_space(3)))
; __device__ __forceinline__ void attn_unit(int bh, int qb, const bf16_t* QKV, const bf16_t* KF, const float* cstab, const float* qg, bf16_t* MIX, LAS unsigned char* lds) {
;     ...
;         const float rs = __builtin_amdgcn_rsqf(ss * (1.0f / 96.0f) + EPS) * C2Q;
; #pragma unroll
;         for (int d0 = 0; d0 < 4; ++d0) { float v[8]; unpack8(raw[d0], v);
; #pragma unroll
;             for (int i = 0; i < 8; ++i) v[i] = v[i] * rs * qg[16 * d0 + 8 * hi + i];
;             qf[d0] = __builtin_bit_cast(bf16x8, pack8(v)); }
;         float x1[8], x2[8], o1[8], o2[8]; unpack8(raw[4], x1); unpack8(raw[5], x2);
; #pragma unroll
;         for (int i = 0; i < 8; ++i) { const float y1 = x1[i] * rs * qg[64 + 8 * hi + i], y2 = x2[i] * rs * qg[80 + 8 * hi + i], co = cs[i], si = cs[16 + i];
;             o1[i] = y1 * co - y2 * si; o2[i] = y1 * si + y2 * co; }
;         qf[4] = __builtin_bit_cast(bf16x8, pack8(o1)); qf[5] = __builtin_bit_cast(bf16x8, pack8(o2));
;     }
;     const char* Kg = (const char*)(KF + (size_t)bh * SEQ * 96);
;     const char* Vg = (const char*)(QKV + (size_t)b * SEQ * 1792 + 768 + h * 128 + 64) + (size_t)(tid >> 3) * 3584 + (tid & 7) * 16;
;     const int kofs0 = (tid / 12) * KROW + (tid % 12) * 16, kofs1 = ((tid + 512) / 12) * KROW + ((tid + 512) % 12) * 16, vofs = KBUF + (tid >> 3) * VROW + (tid & 7) * 16;
;     const int vtb = KBUF + (4 * hi + ((lane & 15) >> 2)) * VROW + (16 * ((lane >> 4) & 1) + 4 * (lane & 3)) * 2;
;     const int NT = 4 * (qb + 1);
;     u32x4 kr0, kr1 = {0u, 0u, 0u, 0u}, vr;
;     ...
;     float mrun = 0.f, lrun = 0.f;
;     f32x16 o0, o1, negm;
; #pragma unroll
;     for (int r = 0; r < 16; ++r) { o0[r] = 0.f; o1[r] = 0.f; negm[r] = 0.f; }
;     ATT_LOAD(0); ATT_WRITE(lds);
;     __syncthreads();
;     for (int t = 0; t < NT; ++t) {
;         LAS unsigned char* buf = lds + (t & 1) * BUFB;
;         if (t + 1 < NT) ATT_LOAD(t + 1);
; #pragma unroll
;         for (int kb = 0; kb < 2; ++kb) {
;             const int key0 = 64 * t + 32 * kb;
;             if (key0 > qw + 31) continue;
;             const LAS unsigned char* kp = buf + (32 * kb + r32) * KROW + 16 * hi;
;             f32x16 p = negm;
;             bf16x8 kfr[6];
; #pragma unroll
;             for (int d0 = 0; d0 < 6; ++d0) kfr[d0] = *(const LAS bf16x8*)(kp + 32 * d0);
;             __builtin_amdgcn_s_setprio(1);
; #pragma unroll
.LBB0_1043:
	s_or_b64 exec, exec, s[4:5]
	v_add_f32_e32 v74, v134, v146
	v_fmamk_f32 v74, v74, 0x3c2aaaab, v232
	v_rsq_f32_e32 v74, v74
	s_mov_b64 s[4:5], 0x680
	v_lshl_add_u64 v[136:137], v[136:137], 0, s[4:5]
	v_lshlrev_b32_e32 v105, 2, v144
	v_mul_f32_e32 v134, 0x3e16c740, v74
	v_pk_mul_f32 v[74:75], v[134:135], v[132:133] op_sel_hi:[0,1]
	v_pk_mul_f32 v[60:61], v[60:61], v[74:75]
	v_pk_mul_f32 v[74:75], v[134:135], v[128:129] op_sel_hi:[0,1]
	v_pk_mul_f32 v[76:77], v[134:135], v[130:131] op_sel_hi:[0,1]
	v_pk_mul_f32 v[56:57], v[56:57], v[74:75]
	v_pk_mul_f32 v[62:63], v[62:63], v[76:77]
	v_cvt_pk_bf16_f32 v76, v56, v57
	v_pk_mul_f32 v[56:57], v[134:135], v[88:89] op_sel_hi:[0,1]
	v_pk_mul_f32 v[52:53], v[56:57], v[52:53]
	v_pk_mul_f32 v[56:57], v[134:135], v[86:87] op_sel_hi:[0,1]
	v_pk_mul_f32 v[54:55], v[56:57], v[54:55]
	v_pk_mul_f32 v[56:57], v[134:135], v[80:81] op_sel_hi:[0,1]
	v_pk_mul_f32 v[48:49], v[56:57], v[48:49]
	v_pk_mul_f32 v[56:57], v[134:135], v[78:79] op_sel_hi:[0,1]
	v_cvt_pk_bf16_f32 v78, v52, v53
	v_add_co_u32_e32 v52, vcc, 0x38000, v136
	v_cvt_pk_bf16_f32 v80, v48, v49
	s_nop 0
	v_addc_co_u32_e32 v53, vcc, 0, v137, vcc
	global_load_dwordx4 v[86:89], v[52:53], off
	v_pk_mul_f32 v[48:49], v[134:135], v[124:125] op_sel_hi:[0,1]
	v_pk_mul_f32 v[44:45], v[48:49], v[44:45]
	v_pk_mul_f32 v[48:49], v[134:135], v[122:123] op_sel_hi:[0,1]
	v_pk_mul_f32 v[46:47], v[48:49], v[46:47]
	v_pk_mul_f32 v[48:49], v[134:135], v[84:85] op_sel_hi:[0,1]
	v_pk_mul_f32 v[40:41], v[48:49], v[40:41]
	v_pk_mul_f32 v[50:51], v[56:57], v[50:51]
	v_cvt_pk_bf16_f32 v84, v40, v41
	v_pk_mul_f32 v[40:41], v[134:135], v[120:121] op_sel_hi:[0,1]
	v_pk_mul_f32 v[20:21], v[40:41], v[20:21]
	v_pk_mul_f32 v[40:41], v[134:135], v[118:119] op_sel_hi:[0,1]
	v_pk_mul_f32 v[22:23], v[40:41], v[22:23]
	v_pk_mul_f32 v[40:41], v[134:135], v[92:93] op_sel_hi:[0,1]
	v_pk_mul_f32 v[16:17], v[40:41], v[16:17]
	v_cvt_pk_bf16_f32 v81, v50, v51
	v_cvt_pk_bf16_f32 v92, v16, v17
	v_pk_mul_f32 v[16:17], v[134:135], v[116:117] op_sel_hi:[0,1]
	v_pk_mul_f32 v[12:13], v[16:17], v[12:13]
	v_pk_mul_f32 v[16:17], v[134:135], v[114:115] op_sel_hi:[0,1]
	v_pk_mul_f32 v[8:9], v[16:17], v[8:9]
	v_pk_mul_f32 v[74:75], v[134:135], v[126:127] op_sel_hi:[0,1]
	v_pk_mul_f32 v[16:17], v[8:9], v[36:37]
	v_pk_mul_f32 v[48:49], v[134:135], v[82:83] op_sel_hi:[0,1]
	v_pk_fma_f32 v[16:17], v[12:13], v[32:33], v[16:17] neg_lo:[0,0,1] neg_hi:[0,0,1]
	v_pk_mul_f32 v[12:13], v[12:13], v[36:37]
	v_pk_mul_f32 v[40:41], v[134:135], v[90:91] op_sel_hi:[0,1]
	v_pk_fma_f32 v[8:9], v[8:9], v[32:33], v[12:13]
	v_pk_mul_f32 v[12:13], v[134:135], v[112:113] op_sel_hi:[0,1]
	v_pk_mul_f32 v[12:13], v[12:13], v[14:15]
	v_pk_mul_f32 v[14:15], v[134:135], v[106:107] op_sel_hi:[0,1]
	v_pk_mul_f32 v[10:11], v[14:15], v[10:11]
	v_pk_mul_f32 v[58:59], v[58:59], v[74:75]
	v_pk_mul_f32 v[14:15], v[10:11], v[38:39]
	v_pk_mul_f32 v[42:43], v[48:49], v[42:43]
	v_pk_fma_f32 v[14:15], v[12:13], v[34:35], v[14:15] neg_lo:[0,0,1] neg_hi:[0,0,1]
	v_pk_mul_f32 v[12:13], v[12:13], v[38:39]
	v_pk_mul_f32 v[18:19], v[40:41], v[18:19]
	v_pk_fma_f32 v[10:11], v[10:11], v[34:35], v[12:13]
	v_pk_mul_f32 v[12:13], v[134:135], v[100:101] op_sel_hi:[0,1]
	v_pk_mul_f32 v[0:1], v[12:13], v[0:1]
	v_pk_mul_f32 v[12:13], v[134:135], v[98:99] op_sel_hi:[0,1]
	v_pk_mul_f32 v[4:5], v[12:13], v[4:5]
	v_mul_u32_u24_e32 v114, 0xd0, v138
	v_pk_mul_f32 v[12:13], v[4:5], v[28:29]
	s_movk_i32 s2, 0xc0
	v_pk_fma_f32 v[12:13], v[0:1], v[24:25], v[12:13] neg_lo:[0,0,1] neg_hi:[0,0,1]
	v_pk_mul_f32 v[0:1], v[0:1], v[28:29]
	v_cvt_pk_bf16_f32 v74, v60, v61
	v_pk_fma_f32 v[0:1], v[4:5], v[24:25], v[0:1]
	v_pk_mul_f32 v[4:5], v[134:135], v[96:97] op_sel_hi:[0,1]
	v_pk_mul_f32 v[2:3], v[4:5], v[2:3]
	v_pk_mul_f32 v[4:5], v[134:135], v[94:95] op_sel_hi:[0,1]
	v_pk_mul_f32 v[4:5], v[4:5], v[6:7]
	v_cvt_pk_bf16_f32 v100, v0, v1
	v_lshrrev_b32_e32 v0, 2, v143
	v_pk_mul_f32 v[6:7], v[4:5], v[30:31]
	v_and_or_b32 v51, v0, 3, v105
	v_and_b32_e32 v0, 16, v143
	v_lshlrev_b32_e32 v1, 2, v143
	v_pk_fma_f32 v[6:7], v[2:3], v[26:27], v[6:7] neg_lo:[0,0,1] neg_hi:[0,0,1]
	v_pk_mul_f32 v[2:3], v[2:3], v[30:31]
	v_and_or_b32 v0, v1, 12, v0
	v_pk_fma_f32 v[2:3], v[4:5], v[26:27], v[2:3]
	v_lshlrev_b32_e32 v115, 1, v0
	v_add_u32_e32 v0, 0, v102
	v_cvt_pk_bf16_f32 v75, v62, v63
	v_cvt_pk_bf16_f32 v77, v58, v59
	v_cvt_pk_bf16_f32 v79, v54, v55
	v_cvt_pk_bf16_f32 v82, v44, v45
	v_cvt_pk_bf16_f32 v83, v46, v47
	v_cvt_pk_bf16_f32 v85, v42, v43
	v_cvt_pk_bf16_f32 v90, v20, v21
	v_cvt_pk_bf16_f32 v91, v22, v23
	v_cvt_pk_bf16_f32 v93, v18, v19
	v_cvt_pk_bf16_f32 v94, v16, v17
	v_cvt_pk_bf16_f32 v95, v14, v15
	v_cvt_pk_bf16_f32 v96, v12, v13
	v_cvt_pk_bf16_f32 v97, v6, v7
	v_cvt_pk_bf16_f32 v98, v8, v9
	v_cvt_pk_bf16_f32 v99, v10, v11
	v_cvt_pk_bf16_f32 v101, v2, v3
	v_mad_u32_u24 v119, v51, s2, 0
	s_cmp_lt_i32 s37, 0
	v_add_u32_e32 v50, v0, v114
	s_cbranch_scc1 .LBB0_1047
	ds_read_b128 v[0:3], v50
	ds_read_b128 v[16:19], v50 offset:32
	ds_read_b128 v[20:23], v50 offset:64
	ds_read_b128 v[24:27], v50 offset:96
	ds_read_b128 v[28:31], v50 offset:128
	ds_read_b128 v[32:35], v50 offset:160
	s_nop 0
	s_waitcnt lgkmcnt(5)
	v_mfma_f32_32x32x16_bf16 v[0:15], v[0:3], v[74:77], 0
	s_waitcnt lgkmcnt(4)
	v_mfma_f32_32x32x16_bf16 v[0:15], v[16:19], v[78:81], v[0:15]
	s_waitcnt lgkmcnt(3)
	v_mfma_f32_32x32x16_bf16 v[0:15], v[20:23], v[82:85], v[0:15]
	s_waitcnt lgkmcnt(2)
	v_mfma_f32_32x32x16_bf16 v[0:15], v[24:27], v[90:93], v[0:15]
	s_waitcnt lgkmcnt(1)
	v_mfma_f32_32x32x16_bf16 v[0:15], v[28:31], v[94:97], v[0:15]
	s_waitcnt lgkmcnt(0)
	v_mfma_f32_32x32x16_bf16 v[0:15], v[32:35], v[98:101], v[0:15]
	s_nop 0
	s_cmp_lg_u32 s37, 0
	s_cbranch_scc1 .LBB0_1046
; __device__ __forceinline__ void attn_unit(int bh, int qb, const bf16_t* QKV, const bf16_t* KF, const float* cstab, const float* qg, bf16_t* MIX, LAS unsigned char* lds) {
;     ...
;             if (key0 + 31 > qw) {
; #pragma unroll
;                 for (int r = 0; r < 16; ++r) { const int key = key0 + (r & 3) + 8 * (r >> 2) + 4 * hi; if (key > q) p[r] = -1e30f; }
;             }
;             float mx = fmaxf(fmaxf(p[0], p[1]), fmaxf(p[2], p[3]));
; #pragma unroll
;             for (int r = 4; r < 16; r += 4) mx = fmaxf(mx, fmaxf(fmaxf(p[r], p[r + 1]), fmaxf(p[r + 2], p[r + 3])));
;             mx = pg8::max32(mx);
;             if (key0 == 0 || __any(mx > 4.0f)) {
;                 const float dl = (key0 == 0) ? mx : fmaxf(mx, 0.f), f = __builtin_amdgcn_exp2f(-dl);
;                 mrun += dl; lrun *= f;
; #pragma unroll
;                 for (int r = 0; r < 16; ++r) { o0[r] *= f; o1[r] *= f; p[r] -= dl; negm[r] = -mrun; }
;             }
;             float ps = 0.f;
; #pragma unroll
;             for (int r = 0; r < 16; ++r) { p[r] = __builtin_amdgcn_exp2f(p[r]); ps += p[r]; }
;             lrun += ps;
;             u32x4 w0, w1;
; #pragma unroll
;             for (int k = 0; k < 4; ++k) { w0[k] = cvt_pk_bf16(p[2 * k], p[2 * k + 1]); w1[k] = cvt_pk_bf16(p[8 + 2 * k], p[8 + 2 * k + 1]); }
;             const bf16x8 pb0 = __builtin_bit_cast(bf16x8, w0), pb1 = __builtin_bit_cast(bf16x8, w1);
;             const LAS unsigned char* vp = buf + vtb + (32 * kb) * VROW;
; #pragma unroll
;             for (int db = 0; db < 2; ++db) {
;                 const v4i16_t a0 = __builtin_amdgcn_ds_read_tr16_b64_v4i16((LAS v4i16_t*)(vp + db * 64));
;                 const v4i16_t a1 = __builtin_amdgcn_ds_read_tr16_b64_v4i16((LAS v4i16_t*)(vp + db * 64 + 8 * VROW));
;                 const v4i16_t c0 = __builtin_amdgcn_ds_read_tr16_b64_v4i16((LAS v4i16_t*)(vp + db * 64 + 16 * VROW));
;                 const v4i16_t c1 = __builtin_amdgcn_ds_read_tr16_b64_v4i16((LAS v4i16_t*)(vp + db * 64 + 24 * VROW));
;                 const bf16x8 va = {a0[0], a0[1], a0[2], a0[3], a1[0], a1[1], a1[2], a1[3]}, vc = {c0[0], c0[1], c0[2], c0[3], c1[0], c1[1], c1[2], c1[3]};
;                 __builtin_amdgcn_s_setprio(1);
;                 if (db == 0) { o0 = MFMA32(va, pb0, o0); o0 = MFMA32(vc, pb1, o0); }
;                 else { o1 = MFMA32(va, pb0, o1); o1 = MFMA32(vc, pb1, o1); }
	v_cmp_lt_i32_e32 vcc, v105, v139
	v_or_b32_e32 v16, 2, v105
	v_or_b32_e32 v17, 3, v105
	s_nop 5
	v_cndmask_b32_e32 v1, v239, v1, vcc
	v_cmp_le_i32_e32 vcc, v105, v139
	v_or_b32_e32 v18, 8, v105
	v_or_b32_e32 v19, 9, v105
	v_cndmask_b32_e32 v0, v239, v0, vcc
	v_cmp_le_i32_e32 vcc, v16, v139
	v_or_b32_e32 v20, 10, v105
	v_or_b32_e32 v21, 11, v105
	v_cndmask_b32_e32 v2, v239, v2, vcc
	v_cmp_le_i32_e32 vcc, v17, v139
	v_or_b32_e32 v22, 16, v105
	v_or_b32_e32 v23, 17, v105
	v_cndmask_b32_e32 v3, v239, v3, vcc
	v_cmp_le_i32_e32 vcc, v18, v139
	v_or_b32_e32 v24, 18, v105
	v_or_b32_e32 v25, 19, v105
	v_cndmask_b32_e32 v4, v239, v4, vcc
	v_cmp_le_i32_e32 vcc, v19, v139
	v_or_b32_e32 v26, 24, v105
	v_or_b32_e32 v27, 25, v105
	v_cndmask_b32_e32 v5, v239, v5, vcc
	v_cmp_le_i32_e32 vcc, v20, v139
	v_or_b32_e32 v28, 26, v105
	v_or_b32_e32 v29, 27, v105
	v_cndmask_b32_e32 v6, v239, v6, vcc
	v_cmp_le_i32_e32 vcc, v21, v139
	s_nop 1
	v_cndmask_b32_e32 v7, v239, v7, vcc
	v_cmp_le_i32_e32 vcc, v22, v139
	s_nop 1
	v_cndmask_b32_e32 v8, v239, v8, vcc
	v_cmp_le_i32_e32 vcc, v23, v139
	s_nop 1
	v_cndmask_b32_e32 v9, v239, v9, vcc
	v_cmp_le_i32_e32 vcc, v24, v139
	s_nop 1
	v_cndmask_b32_e32 v10, v239, v10, vcc
	v_cmp_le_i32_e32 vcc, v25, v139
	s_nop 1
	v_cndmask_b32_e32 v11, v239, v11, vcc
	v_cmp_le_i32_e32 vcc, v26, v139
	s_nop 1
	v_cndmask_b32_e32 v12, v239, v12, vcc
	v_cmp_le_i32_e32 vcc, v27, v139
	s_nop 1
	v_cndmask_b32_e32 v13, v239, v13, vcc
	v_cmp_le_i32_e32 vcc, v28, v139
	s_nop 1
	v_cndmask_b32_e32 v14, v239, v14, vcc
	v_cmp_le_i32_e32 vcc, v29, v139
	s_nop 1
	v_cndmask_b32_e32 v15, v239, v15, vcc
.LBB0_1046:
	s_nop 8
	v_max3_f32 v16, v0, v1, v2
	v_max3_f32 v17, v3, v4, v5
	v_max3_f32 v18, v6, v7, v8
	v_max3_f32 v19, v9, v10, v11
	v_max3_f32 v16, v16, v17, v18
	v_max3_f32 v17, v12, v13, v14
	v_max3_f32 v16, v16, v19, v17
	v_max_f32_e32 v16, v16, v15
	v_mov_b32_e32 v17, v16
	s_nop 1
	v_permlane32_swap_b32_e32 v16, v17
	v_max_f32_e32 v48, v16, v17
	v_sub_f32_e32 v0, v0, v48
	v_sub_f32_e32 v1, v1, v48
	v_exp_f32_e64 v16, -v48
	v_exp_f32_e32 v0, v0
	v_sub_f32_e32 v2, v2, v48
	v_exp_f32_e32 v1, v1
	v_sub_f32_e32 v3, v3, v48
	v_exp_f32_e32 v2, v2
	v_sub_f32_e32 v4, v4, v48
	v_exp_f32_e32 v3, v3
	v_sub_f32_e32 v5, v5, v48
	v_mul_f32_e32 v32, 0, v16
	v_exp_f32_e32 v4, v4
	v_sub_f32_e32 v6, v6, v48
	v_add_f32_e32 v16, v1, v0
	v_exp_f32_e32 v5, v5
	v_sub_f32_e32 v7, v7, v48
	v_add_f32_e32 v16, v2, v16
	v_exp_f32_e32 v6, v6
	v_sub_f32_e32 v8, v8, v48
	v_add_f32_e32 v16, v3, v16
	v_exp_f32_e32 v7, v7
	v_sub_f32_e32 v9, v9, v48
	v_add_f32_e32 v16, v4, v16
	v_exp_f32_e32 v8, v8
	v_sub_f32_e32 v10, v10, v48
	v_add_f32_e32 v16, v5, v16
	v_exp_f32_e32 v9, v9
	v_sub_f32_e32 v11, v11, v48
	v_add_f32_e32 v16, v6, v16
	v_exp_f32_e32 v10, v10
	v_sub_f32_e32 v12, v12, v48
	v_add_f32_e32 v16, v7, v16
	v_exp_f32_e32 v11, v11
	v_sub_f32_e32 v13, v13, v48
	v_add_f32_e32 v16, v8, v16
	v_exp_f32_e32 v12, v12
	v_sub_f32_e32 v14, v14, v48
	v_add_f32_e32 v16, v9, v16
	v_exp_f32_e32 v13, v13
	v_sub_f32_e32 v15, v15, v48
	v_add_f32_e32 v16, v10, v16
	v_exp_f32_e32 v14, v14
	v_add_f32_e32 v16, v11, v16
	v_exp_f32_e32 v15, v15
	v_add_f32_e32 v16, v12, v16
	v_add_f32_e32 v16, v13, v16
	v_add_f32_e32 v16, v14, v16
	v_add_u32_e32 v24, v119, v115
	v_add_f32_e32 v107, v15, v16
	ds_read_b64_tr_b16 v[16:17], v24 offset:13312
	ds_read_b64_tr_b16 v[18:19], v24 offset:14848
	ds_read_b64_tr_b16 v[20:21], v24 offset:16384
	ds_read_b64_tr_b16 v[22:23], v24 offset:17920
	s_movk_i32 s46, 0xc0
	v_mov_b32_e32 v33, v32
	v_mov_b32_e32 v34, v32
	v_mov_b32_e32 v35, v32
	v_mov_b32_e32 v36, v32
	v_mov_b32_e32 v37, v32
	v_mov_b32_e32 v38, v32
	v_mov_b32_e32 v39, v32
	v_mov_b32_e32 v40, v32
	v_mov_b32_e32 v41, v32
	v_mov_b32_e32 v42, v32
	v_mov_b32_e32 v43, v32
	v_mov_b32_e32 v44, v32
	v_mov_b32_e32 v45, v32
	v_mov_b32_e32 v46, v32
	v_mov_b32_e32 v47, v32
	v_cvt_pk_bf16_f32 v52, v0, v1
	v_cvt_pk_bf16_f32 v56, v8, v9
	v_cvt_pk_bf16_f32 v53, v2, v3
	v_cvt_pk_bf16_f32 v57, v10, v11
	v_cvt_pk_bf16_f32 v54, v4, v5
	v_cvt_pk_bf16_f32 v58, v12, v13
	v_cvt_pk_bf16_f32 v55, v6, v7
	v_cvt_pk_bf16_f32 v59, v14, v15
	s_nop 0
	s_waitcnt lgkmcnt(2)
	v_mfma_f32_32x32x16_bf16 v[0:15], v[16:19], v[52:55], v[32:47]
	s_waitcnt lgkmcnt(0)
	v_mfma_f32_32x32x16_bf16 v[0:15], v[20:23], v[56:59], v[0:15]
	s_nop 0
	ds_read_b64_tr_b16 v[60:61], v24 offset:13376
	ds_read_b64_tr_b16 v[62:63], v24 offset:14912
	ds_read_b64_tr_b16 v[120:121], v24 offset:16448
	ds_read_b64_tr_b16 v[122:123], v24 offset:17984
	s_nop 0
	v_mov_b64_e32 v[16:17], v[32:33]
	v_mov_b64_e32 v[18:19], v[34:35]
	v_mov_b64_e32 v[20:21], v[36:37]
	v_mov_b64_e32 v[22:23], v[38:39]
	v_mov_b64_e32 v[24:25], v[40:41]
	v_mov_b64_e32 v[26:27], v[42:43]
	v_mov_b64_e32 v[28:29], v[44:45]
	v_mov_b64_e32 v[30:31], v[46:47]
	s_waitcnt lgkmcnt(2)
	s_nop 0
	v_mfma_f32_32x32x16_bf16 v[16:31], v[60:63], v[52:55], v[16:31]
	s_waitcnt lgkmcnt(0)
	v_mfma_f32_32x32x16_bf16 v[16:31], v[120:123], v[56:59], v[16:31]
	s_nop 0
	v_mov_b32_e32 v49, v32
	v_mov_b32_e32 v106, v65
	v_add_f32_e64 v106, v48, v106
	v_add_f32_e64 v107, v49, v107
	v_xor_b32_e32 v32, 0x80000000, v106
	v_mov_b32_e32 v33, v32
	v_mov_b32_e32 v34, v32
	v_mov_b32_e32 v35, v32
	v_mov_b32_e32 v36, v32
	v_mov_b32_e32 v37, v32
	v_mov_b32_e32 v38, v32
	v_mov_b32_e32 v39, v32
	v_mov_b32_e32 v40, v32
	v_mov_b32_e32 v41, v32
	v_mov_b32_e32 v42, v32
	v_mov_b32_e32 v43, v32
	v_mov_b32_e32 v44, v32
	v_mov_b32_e32 v45, v32
	v_mov_b32_e32 v46, v32
	v_mov_b32_e32 v47, v32
	s_branch .LBB0_1048

; #define LAS __attribute__((address_space(3)))
; #define MFMA32(a, b, c) __builtin_amdgcn_mfma_f32_32x32x16_bf16(a, b, c, 0, 0, 0)
; __device__ __forceinline__ void attn_unit(int bh, int qb, const bf16_t* QKV, const bf16_t* KF, const float* cstab, const float* qg, bf16_t* MIX, LAS unsigned char* lds) {
;     ...
;         for (int kb = 0; kb < 2; ++kb) {
;             const int key0 = 64 * t + 32 * kb;
;             if (key0 > qw + 31) continue;
;             const LAS unsigned char* kp = buf + (32 * kb + r32) * KROW + 16 * hi;
;             f32x16 p = negm;
;             bf16x8 kfr[6];
; #pragma unroll
;             for (int d0 = 0; d0 < 6; ++d0) kfr[d0] = *(const LAS bf16x8*)(kp + 32 * d0);
;             __builtin_amdgcn_s_setprio(1);
; #pragma unroll
;             for (int d0 = 0; d0 < 6; ++d0) p = MFMA32(kfr[d0], qf[d0], p);
;             __builtin_amdgcn_s_setprio(0);
;             if (key0 + 31 > qw) {
; #pragma unroll
;                 for (int r = 0; r < 16; ++r) { const int key = key0 + (r & 3) + 8 * (r >> 2) + 4 * hi; if (key > q) p[r] = -1e30f; }
.LBB0_1048:
	s_or_b32 s2, s37, 31
	v_and_b32_e32 v116, 63, v143
	v_lshlrev_b32_e32 v117, 3, v144
	v_mad_i64_i32 v[112:113], s[4:5], v145, s85, 0
	v_mul_u32_u24_e32 v118, 0xc0, v51
	s_cmp_lt_i32 s2, 32
	s_cbranch_scc1 .LBB0_1054
	ds_read_b128 v[120:123], v50 offset:6656
	ds_read_b128 v[124:127], v50 offset:6688
	ds_read_b128 v[128:131], v50 offset:6720
	ds_read_b128 v[144:147], v50 offset:6752
	ds_read_b128 v[148:151], v50 offset:6784
	ds_read_b128 v[152:155], v50 offset:6816
	s_nop 0
	s_waitcnt lgkmcnt(5)
	v_mfma_f32_32x32x16_bf16 v[48:63], v[120:123], v[74:77], v[32:47]
	s_waitcnt lgkmcnt(4)
	v_mfma_f32_32x32x16_bf16 v[48:63], v[124:127], v[78:81], v[48:63]
	s_waitcnt lgkmcnt(3)
	v_mfma_f32_32x32x16_bf16 v[48:63], v[128:131], v[82:85], v[48:63]
	s_waitcnt lgkmcnt(2)
	v_mfma_f32_32x32x16_bf16 v[48:63], v[144:147], v[90:93], v[48:63]
	s_waitcnt lgkmcnt(1)
	v_mfma_f32_32x32x16_bf16 v[48:63], v[148:151], v[94:97], v[48:63]
	s_waitcnt lgkmcnt(0)
	v_mfma_f32_32x32x16_bf16 v[48:63], v[152:155], v[98:101], v[48:63]
	s_nop 0
	s_cmp_gt_u32 s37, 62
	s_cbranch_scc1 .LBB0_1051
	v_or_b32_e32 v120, 32, v105
	v_cmp_lt_i32_e32 vcc, v120, v139
	s_nop 6
	v_cndmask_b32_e32 v49, v239, v49, vcc
	v_cmp_le_i32_e32 vcc, v120, v139
	v_or_b32_e32 v120, 34, v105
	s_nop 0
	v_cndmask_b32_e32 v48, v239, v48, vcc
	v_cmp_le_i32_e32 vcc, v120, v139
	v_or_b32_e32 v120, 35, v105
	s_nop 0
	v_cndmask_b32_e32 v50, v239, v50, vcc
	v_cmp_le_i32_e32 vcc, v120, v139
	v_or_b32_e32 v120, 40, v105
	s_nop 0
	v_cndmask_b32_e32 v51, v239, v51, vcc
	v_cmp_le_i32_e32 vcc, v120, v139
	v_or_b32_e32 v120, 41, v105
	s_nop 0
	v_cndmask_b32_e32 v52, v239, v52, vcc
	v_cmp_le_i32_e32 vcc, v120, v139
	v_or_b32_e32 v120, 42, v105
	s_nop 0
	v_cndmask_b32_e32 v53, v239, v53, vcc
	v_cmp_le_i32_e32 vcc, v120, v139
	v_or_b32_e32 v120, 43, v105
	s_nop 0
	v_cndmask_b32_e32 v54, v239, v54, vcc
	v_cmp_le_i32_e32 vcc, v120, v139
	v_or_b32_e32 v120, 48, v105
	s_nop 0
	v_cndmask_b32_e32 v55, v239, v55, vcc
	v_cmp_le_i32_e32 vcc, v120, v139
	v_or_b32_e32 v120, 49, v105
	s_nop 0
	v_cndmask_b32_e32 v56, v239, v56, vcc
	v_cmp_le_i32_e32 vcc, v120, v139
	v_or_b32_e32 v120, 50, v105
	s_nop 0
	v_cndmask_b32_e32 v57, v239, v57, vcc
	v_cmp_le_i32_e32 vcc, v120, v139
	v_or_b32_e32 v120, 51, v105
	s_nop 0
	v_cndmask_b32_e32 v58, v239, v58, vcc
	v_cmp_le_i32_e32 vcc, v120, v139
	v_or_b32_e32 v120, 56, v105
	s_nop 0
	v_cndmask_b32_e32 v59, v239, v59, vcc
	v_cmp_le_i32_e32 vcc, v120, v139
	v_or_b32_e32 v120, 57, v105
	s_nop 0
	v_cndmask_b32_e32 v60, v239, v60, vcc
	v_cmp_le_i32_e32 vcc, v120, v139
	v_or_b32_e32 v120, 58, v105
	s_nop 0
	v_cndmask_b32_e32 v61, v239, v61, vcc
	v_cmp_le_i32_e32 vcc, v120, v139
	v_or_b32_e32 v120, 59, v105
	s_nop 0
	v_cndmask_b32_e32 v62, v239, v62, vcc
	v_cmp_le_i32_e32 vcc, v120, v139
	s_nop 1
	v_cndmask_b32_e32 v63, v239, v63, vcc

; __device__ __forceinline__ unsigned cvt_pk_bf16(float lo, float hi) { const f32x2c_ v = {lo, hi}; const bf16x2c_ b = __builtin_convertvector(v, bf16x2c_); return __builtin_bit_cast(unsigned, b); }
; #define LAS __attribute__((address_space(3)))
; #define MFMA32(a, b, c) __builtin_amdgcn_mfma_f32_32x32x16_bf16(a, b, c, 0, 0, 0)
; __device__ __forceinline__ void attn_unit(int bh, int qb, const bf16_t* QKV, const bf16_t* KF, const float* cstab, const float* qg, bf16_t* MIX, LAS unsigned char* lds) {
;     ...
;             float ps = 0.f;
; #pragma unroll
;             for (int r = 0; r < 16; ++r) { p[r] = __builtin_amdgcn_exp2f(p[r]); ps += p[r]; }
;             lrun += ps;
;             u32x4 w0, w1;
; #pragma unroll
;             for (int k = 0; k < 4; ++k) { w0[k] = cvt_pk_bf16(p[2 * k], p[2 * k + 1]); w1[k] = cvt_pk_bf16(p[8 + 2 * k], p[8 + 2 * k + 1]); }
;             const bf16x8 pb0 = __builtin_bit_cast(bf16x8, w0), pb1 = __builtin_bit_cast(bf16x8, w1);
;             const LAS unsigned char* vp = buf + vtb + (32 * kb) * VROW;
; #pragma unroll
;             for (int db = 0; db < 2; ++db) {
;                 const v4i16_t a0 = __builtin_amdgcn_ds_read_tr16_b64_v4i16((LAS v4i16_t*)(vp + db * 64));
;                 const v4i16_t a1 = __builtin_amdgcn_ds_read_tr16_b64_v4i16((LAS v4i16_t*)(vp + db * 64 + 8 * VROW));
;                 const v4i16_t c0 = __builtin_amdgcn_ds_read_tr16_b64_v4i16((LAS v4i16_t*)(vp + db * 64 + 16 * VROW));
;                 const v4i16_t c1 = __builtin_amdgcn_ds_read_tr16_b64_v4i16((LAS v4i16_t*)(vp + db * 64 + 24 * VROW));
;                 const bf16x8 va = {a0[0], a0[1], a0[2], a0[3], a1[0], a1[1], a1[2], a1[3]}, vc = {c0[0], c0[1], c0[2], c0[3], c1[0], c1[1], c1[2], c1[3]};
;                 __builtin_amdgcn_s_setprio(1);
;                 if (db == 0) { o0 = MFMA32(va, pb0, o0); o0 = MFMA32(vc, pb1, o0); }
;                 else { o1 = MFMA32(va, pb0, o1); o1 = MFMA32(vc, pb1, o1); }
;                 __builtin_amdgcn_s_setprio(0);
;             }
.LBB0_1053:
	v_exp_f32_e32 v48, v48
	v_exp_f32_e32 v49, v49
	v_exp_f32_e32 v50, v50
	v_exp_f32_e32 v51, v51
	v_exp_f32_e32 v121, v52
	v_add_f32_e32 v120, v49, v48
	v_add_f32_e32 v120, v50, v120
	v_add_f32_e32 v120, v51, v120
	v_add_f32_e32 v52, v121, v120
	v_exp_f32_e32 v120, v53
	v_exp_f32_e32 v122, v54
	v_exp_f32_e32 v55, v55
	v_exp_f32_e32 v53, v56
	v_add_f32_e32 v52, v120, v52
	v_exp_f32_e32 v54, v57
	v_add_f32_e32 v52, v122, v52
	v_exp_f32_e32 v56, v58
	v_add_f32_e32 v52, v55, v52
	v_exp_f32_e32 v57, v59
	v_add_f32_e32 v52, v53, v52
	v_exp_f32_e32 v58, v60
	v_add_f32_e32 v52, v54, v52
	v_exp_f32_e32 v59, v61
	v_add_f32_e32 v52, v56, v52
	v_exp_f32_e32 v60, v62
	v_add_f32_e32 v52, v57, v52
	v_exp_f32_e32 v61, v63
	v_add_f32_e32 v52, v58, v52
	v_add_f32_e32 v52, v59, v52
	v_add_f32_e32 v52, v60, v52
	v_add_u32_e32 v119, v119, v115
	v_add_f32_e32 v123, v61, v52
	v_cvt_pk_bf16_f32 v48, v48, v49
	v_cvt_pk_bf16_f32 v52, v53, v54
	v_cvt_pk_bf16_f32 v49, v50, v51
	v_cvt_pk_bf16_f32 v53, v56, v57
	v_cvt_pk_bf16_f32 v54, v58, v59
	v_cvt_pk_bf16_f32 v51, v122, v55
	v_cvt_pk_bf16_f32 v55, v60, v61
	ds_read_b64_tr_b16 v[56:57], v119 offset:19456
	ds_read_b64_tr_b16 v[58:59], v119 offset:20992
	ds_read_b64_tr_b16 v[60:61], v119 offset:22528
	ds_read_b64_tr_b16 v[62:63], v119 offset:24064
	v_cvt_pk_bf16_f32 v50, v121, v120
	s_nop 0
	s_waitcnt lgkmcnt(2)
	v_mfma_f32_32x32x16_bf16 v[0:15], v[56:59], v[48:51], v[0:15]
	s_waitcnt lgkmcnt(0)
	v_mfma_f32_32x32x16_bf16 v[0:15], v[60:63], v[52:55], v[0:15]
	s_nop 0
	ds_read_b64_tr_b16 v[56:57], v119 offset:19520
	ds_read_b64_tr_b16 v[58:59], v119 offset:21056
	ds_read_b64_tr_b16 v[60:61], v119 offset:22592
	ds_read_b64_tr_b16 v[62:63], v119 offset:24128
	s_nop 0
	s_waitcnt lgkmcnt(2)
	v_mfma_f32_32x32x16_bf16 v[16:31], v[56:59], v[48:51], v[16:31]
	s_waitcnt lgkmcnt(0)
	v_mfma_f32_32x32x16_bf16 v[16:31], v[60:63], v[52:55], v[16:31]
	s_nop 0
	v_add_f32_e32 v107, v107, v123

; #define LAS __attribute__((address_space(3)))
; #define MFMA32(a, b, c) __builtin_amdgcn_mfma_f32_32x32x16_bf16(a, b, c, 0, 0, 0)
; #define ATT_LOAD(t) do { kr0 = *(const u32x4*)(Kg + (size_t)(t) * 12288 + tid * 16); if (tid < 256) kr1 = *(const u32x4*)(Kg + (size_t)(t) * 12288 + (tid + 512) * 16); vr = *(const u32x4*)(Vg + (size_t)(t) * (64 * 3584)); } while (0)
; __device__ __forceinline__ void attn_unit(int bh, int qb, const bf16_t* QKV, const bf16_t* KF, const float* cstab, const float* qg, bf16_t* MIX, LAS unsigned char* lds) {
;     ...
;         LAS unsigned char* buf = lds + (t & 1) * BUFB;
;         if (t + 1 < NT) ATT_LOAD(t + 1);
; #pragma unroll
;         for (int kb = 0; kb < 2; ++kb) {
;             const int key0 = 64 * t + 32 * kb;
;             if (key0 > qw + 31) continue;
;             const LAS unsigned char* kp = buf + (32 * kb + r32) * KROW + 16 * hi;
;             f32x16 p = negm;
;             bf16x8 kfr[6];
; #pragma unroll
;             for (int d0 = 0; d0 < 6; ++d0) kfr[d0] = *(const LAS bf16x8*)(kp + 32 * d0);
;             __builtin_amdgcn_s_setprio(1);
; #pragma unroll
;             for (int d0 = 0; d0 < 6; ++d0) p = MFMA32(kfr[d0], qf[d0], p);
;             __builtin_amdgcn_s_setprio(0);
;             if (key0 + 31 > qw) {
; #pragma unroll
;                 for (int r = 0; r < 16; ++r) { const int key = key0 + (r & 3) + 8 * (r >> 2) + 4 * hi; if (key > q) p[r] = -1e30f; }
.LBB0_1061:
	s_and_b32 s23, 1, s40
	s_cselect_b32 s22, 0, 0x6400
	s_add_i32 s44, s22, 0
	s_add_i32 s22, s43, 64
	v_add_u32_e32 v48, s44, v102
	v_add_u32_e32 v119, s44, v118
	s_cmp_gt_i32 s22, s2
	v_add_u32_e32 v120, v48, v114
	s_cbranch_scc1 .LBB0_1068
	ds_read_b128 v[122:125], v120
	ds_read_b128 v[126:129], v120 offset:32
	ds_read_b128 v[130:133], v120 offset:64
	ds_read_b128 v[140:143], v120 offset:96
	ds_read_b128 v[144:147], v120 offset:128
	ds_read_b128 v[148:151], v120 offset:160
	s_nop 0
	s_waitcnt lgkmcnt(5)
	v_mfma_f32_32x32x16_bf16 v[48:63], v[122:125], v[74:77], v[32:47]
	s_waitcnt lgkmcnt(4)
	v_mfma_f32_32x32x16_bf16 v[48:63], v[126:129], v[78:81], v[48:63]
	s_waitcnt lgkmcnt(3)
	v_mfma_f32_32x32x16_bf16 v[48:63], v[130:133], v[82:85], v[48:63]
	s_waitcnt lgkmcnt(2)
	v_mfma_f32_32x32x16_bf16 v[48:63], v[140:143], v[90:93], v[48:63]
	s_waitcnt lgkmcnt(1)
	v_mfma_f32_32x32x16_bf16 v[48:63], v[144:147], v[94:97], v[48:63]
	s_waitcnt lgkmcnt(0)
	v_mfma_f32_32x32x16_bf16 v[48:63], v[148:151], v[98:101], v[48:63]
	v_add_u32_e32 v172, v119, v115
	ds_read_b64_tr_b16 v[156:157], v172 offset:13312
	ds_read_b64_tr_b16 v[158:159], v172 offset:14848
	ds_read_b64_tr_b16 v[160:161], v172 offset:16384
	ds_read_b64_tr_b16 v[162:163], v172 offset:17920
	ds_read_b64_tr_b16 v[164:165], v172 offset:13376
	ds_read_b64_tr_b16 v[166:167], v172 offset:14912
	ds_read_b64_tr_b16 v[168:169], v172 offset:16448
	ds_read_b64_tr_b16 v[170:171], v172 offset:17984
	ds_read_b128 v[202:205], v120 offset:6656
	ds_read_b128 v[206:209], v120 offset:6688
	ds_read_b128 v[210:213], v120 offset:6720
	ds_read_b128 v[214:217], v120 offset:6752
	ds_read_b128 v[218:221], v120 offset:6784
	ds_read_b128 v[222:225], v120 offset:6816
	s_nop 0
	s_add_i32 s44, s43, 0x5f
	s_cmp_le_i32 s44, s37
	s_cbranch_scc1 .LBB0_1064
	v_add_u32_e32 v121, s43, v105
	v_add_u32_e32 v122, 64, v121
	v_cmp_lt_i32_e32 vcc, v122, v139
	s_nop 4
	v_cndmask_b32_e32 v49, v239, v49, vcc
	v_cmp_le_i32_e32 vcc, v122, v139
	v_add_u32_e32 v122, 0x42, v121
	s_nop 0
	v_cndmask_b32_e32 v48, v239, v48, vcc
	v_cmp_le_i32_e32 vcc, v122, v139
	v_add_u32_e32 v122, 0x43, v121
	s_nop 0
	v_cndmask_b32_e32 v50, v239, v50, vcc
	v_cmp_le_i32_e32 vcc, v122, v139
	v_add_u32_e32 v122, 0x48, v121
	s_nop 0
	v_cndmask_b32_e32 v51, v239, v51, vcc
	v_cmp_le_i32_e32 vcc, v122, v139
	v_add_u32_e32 v122, 0x49, v121
	s_nop 0
	v_cndmask_b32_e32 v52, v239, v52, vcc
	v_cmp_le_i32_e32 vcc, v122, v139
	v_add_u32_e32 v122, 0x4a, v121
	s_nop 0
	v_cndmask_b32_e32 v53, v239, v53, vcc
	v_cmp_le_i32_e32 vcc, v122, v139
	v_add_u32_e32 v122, 0x4b, v121
	s_nop 0
	v_cndmask_b32_e32 v54, v239, v54, vcc
	v_cmp_le_i32_e32 vcc, v122, v139
	v_add_u32_e32 v122, 0x50, v121
	s_nop 0
	v_cndmask_b32_e32 v55, v239, v55, vcc
	v_cmp_le_i32_e32 vcc, v122, v139
	v_add_u32_e32 v122, 0x51, v121
	s_nop 0
	v_cndmask_b32_e32 v56, v239, v56, vcc
	v_cmp_le_i32_e32 vcc, v122, v139
	v_add_u32_e32 v122, 0x52, v121
	s_nop 0
	v_cndmask_b32_e32 v57, v239, v57, vcc
	v_cmp_le_i32_e32 vcc, v122, v139
	v_add_u32_e32 v122, 0x53, v121
	s_nop 0
	v_cndmask_b32_e32 v58, v239, v58, vcc
	v_cmp_le_i32_e32 vcc, v122, v139
	v_add_u32_e32 v122, 0x58, v121
	s_nop 0
	v_cndmask_b32_e32 v59, v239, v59, vcc
	v_cmp_le_i32_e32 vcc, v122, v139
	v_add_u32_e32 v122, 0x59, v121
	s_nop 0
	v_cndmask_b32_e32 v60, v239, v60, vcc
	v_cmp_le_i32_e32 vcc, v122, v139
	v_add_u32_e32 v122, 0x5a, v121
	v_add_u32_e32 v121, 0x5b, v121
	v_cndmask_b32_e32 v61, v239, v61, vcc
	v_cmp_le_i32_e32 vcc, v122, v139
	s_nop 1
	v_cndmask_b32_e32 v62, v239, v62, vcc
	v_cmp_le_i32_e32 vcc, v121, v139
	s_nop 1
	v_cndmask_b32_e32 v63, v239, v63, vcc

; __device__ __forceinline__ unsigned cvt_pk_bf16(float lo, float hi) { const f32x2c_ v = {lo, hi}; const bf16x2c_ b = __builtin_convertvector(v, bf16x2c_); return __builtin_bit_cast(unsigned, b); }
; #define LAS __attribute__((address_space(3)))
; #define MFMA32(a, b, c) __builtin_amdgcn_mfma_f32_32x32x16_bf16(a, b, c, 0, 0, 0)
; __device__ __forceinline__ void attn_unit(int bh, int qb, const bf16_t* QKV, const bf16_t* KF, const float* cstab, const float* qg, bf16_t* MIX, LAS unsigned char* lds) {
;     ...
;             float ps = 0.f;
; #pragma unroll
;             for (int r = 0; r < 16; ++r) { p[r] = __builtin_amdgcn_exp2f(p[r]); ps += p[r]; }
;             lrun += ps;
;             u32x4 w0, w1;
; #pragma unroll
;             for (int k = 0; k < 4; ++k) { w0[k] = cvt_pk_bf16(p[2 * k], p[2 * k + 1]); w1[k] = cvt_pk_bf16(p[8 + 2 * k], p[8 + 2 * k + 1]); }
;             const bf16x8 pb0 = __builtin_bit_cast(bf16x8, w0), pb1 = __builtin_bit_cast(bf16x8, w1);
;             const LAS unsigned char* vp = buf + vtb + (32 * kb) * VROW;
; #pragma unroll
;             for (int db = 0; db < 2; ++db) {
;                 const v4i16_t a0 = __builtin_amdgcn_ds_read_tr16_b64_v4i16((LAS v4i16_t*)(vp + db * 64));
;                 const v4i16_t a1 = __builtin_amdgcn_ds_read_tr16_b64_v4i16((LAS v4i16_t*)(vp + db * 64 + 8 * VROW));
;                 const v4i16_t c0 = __builtin_amdgcn_ds_read_tr16_b64_v4i16((LAS v4i16_t*)(vp + db * 64 + 16 * VROW));
;                 const v4i16_t c1 = __builtin_amdgcn_ds_read_tr16_b64_v4i16((LAS v4i16_t*)(vp + db * 64 + 24 * VROW));
;                 const bf16x8 va = {a0[0], a0[1], a0[2], a0[3], a1[0], a1[1], a1[2], a1[3]}, vc = {c0[0], c0[1], c0[2], c0[3], c1[0], c1[1], c1[2], c1[3]};
;                 __builtin_amdgcn_s_setprio(1);
;                 if (db == 0) { o0 = MFMA32(va, pb0, o0); o0 = MFMA32(vc, pb1, o0); }
;                 else { o1 = MFMA32(va, pb0, o1); o1 = MFMA32(vc, pb1, o1); }
;                 __builtin_amdgcn_s_setprio(0);
;             }
.LBB0_1066:
	v_exp_f32_e32 v48, v48
	v_exp_f32_e32 v49, v49
	v_exp_f32_e32 v50, v50
	v_exp_f32_e32 v51, v51
	v_exp_f32_e32 v122, v52
	v_add_f32_e32 v121, v49, v48
	v_add_f32_e32 v121, v50, v121
	v_add_f32_e32 v121, v51, v121
	v_add_f32_e32 v52, v122, v121
	v_exp_f32_e32 v121, v53
	v_exp_f32_e32 v123, v54
	v_exp_f32_e32 v55, v55
	v_exp_f32_e32 v53, v56
	v_add_f32_e32 v52, v121, v52
	v_exp_f32_e32 v54, v57
	v_add_f32_e32 v52, v123, v52
	v_exp_f32_e32 v56, v58
	v_add_f32_e32 v52, v55, v52
	v_exp_f32_e32 v57, v59
	v_add_f32_e32 v52, v53, v52
	v_exp_f32_e32 v58, v60
	v_add_f32_e32 v52, v54, v52
	v_exp_f32_e32 v59, v61
	v_add_f32_e32 v52, v56, v52
	v_exp_f32_e32 v60, v62
	v_add_f32_e32 v52, v57, v52
	v_exp_f32_e32 v61, v63
	v_add_f32_e32 v52, v58, v52
	v_add_f32_e32 v52, v59, v52
	v_add_f32_e32 v52, v60, v52
	v_cvt_pk_bf16_f32 v48, v48, v49
	v_cvt_pk_bf16_f32 v49, v50, v51
	v_cvt_pk_bf16_f32 v50, v122, v121
	v_add_f32_e32 v124, v61, v52
	v_cvt_pk_bf16_f32 v52, v53, v54
	v_cvt_pk_bf16_f32 v53, v56, v57
	v_cvt_pk_bf16_f32 v54, v58, v59
	v_cvt_pk_bf16_f32 v51, v123, v55
	v_cvt_pk_bf16_f32 v55, v60, v61
	s_nop 0
	s_waitcnt lgkmcnt(12)
	v_mfma_f32_32x32x16_bf16 v[0:15], v[156:159], v[48:51], v[0:15]
	s_waitcnt lgkmcnt(10)
	v_mfma_f32_32x32x16_bf16 v[0:15], v[160:163], v[52:55], v[0:15]
	s_nop 0
	s_nop 0
	s_waitcnt lgkmcnt(8)
	v_mfma_f32_32x32x16_bf16 v[16:31], v[164:167], v[48:51], v[16:31]
	s_waitcnt lgkmcnt(6)
	v_mfma_f32_32x32x16_bf16 v[16:31], v[168:171], v[52:55], v[16:31]
	s_nop 0
	v_add_f32_e32 v107, v107, v124
	s_add_i32 s44, s43, 0x60
	s_cmp_gt_i32 s44, s2
	s_cbranch_scc0 .LBB0_1069

; __device__ __forceinline__ void attn_unit(int bh, int qb, const bf16_t* QKV, const bf16_t* KF, const float* cstab, const float* qg, bf16_t* MIX, LAS unsigned char* lds) {
;     ...
;             if (key0 > qw + 31) continue;
;             const LAS unsigned char* kp = buf + (32 * kb + r32) * KROW + 16 * hi;
;             f32x16 p = negm;
;             bf16x8 kfr[6];
; #pragma unroll
;             for (int d0 = 0; d0 < 6; ++d0) kfr[d0] = *(const LAS bf16x8*)(kp + 32 * d0);
;             __builtin_amdgcn_s_setprio(1);
; #pragma unroll
;             for (int d0 = 0; d0 < 6; ++d0) p = MFMA32(kfr[d0], qf[d0], p);
;             __builtin_amdgcn_s_setprio(0);
;             if (key0 + 31 > qw) {
; #pragma unroll
;                 for (int r = 0; r < 16; ++r) { const int key = key0 + (r & 3) + 8 * (r >> 2) + 4 * hi; if (key > q) p[r] = -1e30f; }
;             }
;             float mx = fmaxf(fmaxf(p[0], p[1]), fmaxf(p[2], p[3]));
; #pragma unroll
;             for (int r = 4; r < 16; r += 4) mx = fmaxf(mx, fmaxf(fmaxf(p[r], p[r + 1]), fmaxf(p[r + 2], p[r + 3])));
;             mx = pg8::max32(mx);
;             if (key0 == 0 || __any(mx > 4.0f)) {
;                 const float dl = (key0 == 0) ? mx : fmaxf(mx, 0.f), f = __builtin_amdgcn_exp2f(-dl);
;                 mrun += dl; lrun *= f;
; #pragma unroll
;                 for (int r = 0; r < 16; ++r) { o0[r] *= f; o1[r] *= f; p[r] -= dl; negm[r] = -mrun; }
;             }
;             float ps = 0.f;
; #pragma unroll
;             for (int r = 0; r < 16; ++r) { p[r] = __builtin_amdgcn_exp2f(p[r]); ps += p[r]; }
;             lrun += ps;
;             u32x4 w0, w1;
; #pragma unroll
;             for (int k = 0; k < 4; ++k) { w0[k] = cvt_pk_bf16(p[2 * k], p[2 * k + 1]); w1[k] = cvt_pk_bf16(p[8 + 2 * k], p[8 + 2 * k + 1]); }
;             const bf16x8 pb0 = __builtin_bit_cast(bf16x8, w0), pb1 = __builtin_bit_cast(bf16x8, w1);
;             const LAS unsigned char* vp = buf + vtb + (32 * kb) * VROW;
; #pragma unroll
;             for (int db = 0; db < 2; ++db) {
;                 const v4i16_t a0 = __builtin_amdgcn_ds_read_tr16_b64_v4i16((LAS v4i16_t*)(vp + db * 64));
;                 const v4i16_t a1 = __builtin_amdgcn_ds_read_tr16_b64_v4i16((LAS v4i16_t*)(vp + db * 64 + 8 * VROW));
;                 const v4i16_t c0 = __builtin_amdgcn_ds_read_tr16_b64_v4i16((LAS v4i16_t*)(vp + db * 64 + 16 * VROW));
.LBB0_1069:
	s_nop 0
	s_waitcnt lgkmcnt(5)
	v_mfma_f32_32x32x16_bf16 v[48:63], v[202:205], v[74:77], v[32:47]
	s_waitcnt lgkmcnt(4)
	v_mfma_f32_32x32x16_bf16 v[48:63], v[206:209], v[78:81], v[48:63]
	s_waitcnt lgkmcnt(3)
	v_mfma_f32_32x32x16_bf16 v[48:63], v[210:213], v[82:85], v[48:63]
	s_waitcnt lgkmcnt(2)
	v_mfma_f32_32x32x16_bf16 v[48:63], v[214:217], v[90:93], v[48:63]
	s_waitcnt lgkmcnt(1)
	v_mfma_f32_32x32x16_bf16 v[48:63], v[218:221], v[94:97], v[48:63]
	s_waitcnt lgkmcnt(0)
	v_mfma_f32_32x32x16_bf16 v[48:63], v[222:225], v[98:101], v[48:63]
	v_add_u32_e32 v172, v119, v115
	ds_read_b64_tr_b16 v[156:157], v172 offset:19456
	ds_read_b64_tr_b16 v[158:159], v172 offset:20992
	ds_read_b64_tr_b16 v[160:161], v172 offset:22528
	ds_read_b64_tr_b16 v[162:163], v172 offset:24064
	ds_read_b64_tr_b16 v[164:165], v172 offset:19520
	ds_read_b64_tr_b16 v[166:167], v172 offset:21056
	ds_read_b64_tr_b16 v[168:169], v172 offset:22592
	ds_read_b64_tr_b16 v[170:171], v172 offset:24128
	s_nop 0
	s_add_i32 s44, s43, 0x7f
	s_cmp_le_i32 s44, s37
	s_cbranch_scc1 .LBB0_1071
	v_add_u32_e32 v120, s43, v105
	v_add_u32_e32 v121, 0x60, v120
	v_cmp_lt_i32_e32 vcc, v121, v139
	s_nop 4
	v_cndmask_b32_e32 v49, v239, v49, vcc
	v_cmp_le_i32_e32 vcc, v121, v139
	v_add_u32_e32 v121, 0x62, v120
	s_nop 0
	v_cndmask_b32_e32 v48, v239, v48, vcc
	v_cmp_le_i32_e32 vcc, v121, v139
	v_add_u32_e32 v121, 0x63, v120
	s_nop 0
	v_cndmask_b32_e32 v50, v239, v50, vcc
	v_cmp_le_i32_e32 vcc, v121, v139
	v_add_u32_e32 v121, 0x68, v120
	s_nop 0
	v_cndmask_b32_e32 v51, v239, v51, vcc
	v_cmp_le_i32_e32 vcc, v121, v139
	v_add_u32_e32 v121, 0x69, v120
	s_nop 0
	v_cndmask_b32_e32 v52, v239, v52, vcc
	v_cmp_le_i32_e32 vcc, v121, v139
	v_add_u32_e32 v121, 0x6a, v120
	s_nop 0
	v_cndmask_b32_e32 v53, v239, v53, vcc
	v_cmp_le_i32_e32 vcc, v121, v139
	v_add_u32_e32 v121, 0x6b, v120
	s_nop 0
	v_cndmask_b32_e32 v54, v239, v54, vcc
	v_cmp_le_i32_e32 vcc, v121, v139
	v_add_u32_e32 v121, 0x70, v120
	s_nop 0
	v_cndmask_b32_e32 v55, v239, v55, vcc
	v_cmp_le_i32_e32 vcc, v121, v139
	v_add_u32_e32 v121, 0x71, v120
	s_nop 0
	v_cndmask_b32_e32 v56, v239, v56, vcc
	v_cmp_le_i32_e32 vcc, v121, v139
	v_add_u32_e32 v121, 0x72, v120
	s_nop 0
	v_cndmask_b32_e32 v57, v239, v57, vcc
	v_cmp_le_i32_e32 vcc, v121, v139
	v_add_u32_e32 v121, 0x73, v120
	s_nop 0
	v_cndmask_b32_e32 v58, v239, v58, vcc
	v_cmp_le_i32_e32 vcc, v121, v139
	v_add_u32_e32 v121, 0x78, v120
	s_nop 0
	v_cndmask_b32_e32 v59, v239, v59, vcc
	v_cmp_le_i32_e32 vcc, v121, v139
	v_add_u32_e32 v121, 0x79, v120
	s_nop 0
	v_cndmask_b32_e32 v60, v239, v60, vcc
	v_cmp_le_i32_e32 vcc, v121, v139
	v_add_u32_e32 v121, 0x7a, v120
	v_add_u32_e32 v120, 0x7b, v120
	v_cndmask_b32_e32 v61, v239, v61, vcc
	v_cmp_le_i32_e32 vcc, v121, v139
	s_nop 1
	v_cndmask_b32_e32 v62, v239, v62, vcc
	v_cmp_le_i32_e32 vcc, v120, v139
	s_nop 1
	v_cndmask_b32_e32 v63, v239, v63, vcc

; __device__ __forceinline__ unsigned cvt_pk_bf16(float lo, float hi) { const f32x2c_ v = {lo, hi}; const bf16x2c_ b = __builtin_convertvector(v, bf16x2c_); return __builtin_bit_cast(unsigned, b); }
; #define LAS __attribute__((address_space(3)))
; #define MFMA32(a, b, c) __builtin_amdgcn_mfma_f32_32x32x16_bf16(a, b, c, 0, 0, 0)
; __device__ __forceinline__ void attn_unit(int bh, int qb, const bf16_t* QKV, const bf16_t* KF, const float* cstab, const float* qg, bf16_t* MIX, LAS unsigned char* lds) {
;     ...
;             float ps = 0.f;
; #pragma unroll
;             for (int r = 0; r < 16; ++r) { p[r] = __builtin_amdgcn_exp2f(p[r]); ps += p[r]; }
;             lrun += ps;
;             u32x4 w0, w1;
; #pragma unroll
;             for (int k = 0; k < 4; ++k) { w0[k] = cvt_pk_bf16(p[2 * k], p[2 * k + 1]); w1[k] = cvt_pk_bf16(p[8 + 2 * k], p[8 + 2 * k + 1]); }
;             const bf16x8 pb0 = __builtin_bit_cast(bf16x8, w0), pb1 = __builtin_bit_cast(bf16x8, w1);
;             const LAS unsigned char* vp = buf + vtb + (32 * kb) * VROW;
; #pragma unroll
;             for (int db = 0; db < 2; ++db) {
;                 const v4i16_t a0 = __builtin_amdgcn_ds_read_tr16_b64_v4i16((LAS v4i16_t*)(vp + db * 64));
;                 const v4i16_t a1 = __builtin_amdgcn_ds_read_tr16_b64_v4i16((LAS v4i16_t*)(vp + db * 64 + 8 * VROW));
;                 const v4i16_t c0 = __builtin_amdgcn_ds_read_tr16_b64_v4i16((LAS v4i16_t*)(vp + db * 64 + 16 * VROW));
;                 const v4i16_t c1 = __builtin_amdgcn_ds_read_tr16_b64_v4i16((LAS v4i16_t*)(vp + db * 64 + 24 * VROW));
;                 const bf16x8 va = {a0[0], a0[1], a0[2], a0[3], a1[0], a1[1], a1[2], a1[3]}, vc = {c0[0], c0[1], c0[2], c0[3], c1[0], c1[1], c1[2], c1[3]};
;                 __builtin_amdgcn_s_setprio(1);
;                 if (db == 0) { o0 = MFMA32(va, pb0, o0); o0 = MFMA32(vc, pb1, o0); }
;                 else { o1 = MFMA32(va, pb0, o1); o1 = MFMA32(vc, pb1, o1); }
;                 __builtin_amdgcn_s_setprio(0);
;             }
.LBB0_1073:
	v_exp_f32_e32 v48, v48
	v_exp_f32_e32 v49, v49
	v_exp_f32_e32 v50, v50
	v_exp_f32_e32 v51, v51
	v_exp_f32_e32 v121, v52
	v_add_f32_e32 v120, v49, v48
	v_add_f32_e32 v120, v50, v120
	v_add_f32_e32 v120, v51, v120
	v_add_f32_e32 v52, v121, v120
	v_exp_f32_e32 v120, v53
	v_exp_f32_e32 v122, v54
	v_exp_f32_e32 v55, v55
	v_exp_f32_e32 v53, v56
	v_add_f32_e32 v52, v120, v52
	v_exp_f32_e32 v54, v57
	v_add_f32_e32 v52, v122, v52
	v_exp_f32_e32 v56, v58
	v_add_f32_e32 v52, v55, v52
	v_exp_f32_e32 v57, v59
	v_add_f32_e32 v52, v53, v52
	v_exp_f32_e32 v58, v60
	v_add_f32_e32 v52, v54, v52
	v_exp_f32_e32 v59, v61
	v_add_f32_e32 v52, v56, v52
	v_exp_f32_e32 v60, v62
	v_add_f32_e32 v52, v57, v52
	v_exp_f32_e32 v61, v63
	v_add_f32_e32 v52, v58, v52
	v_add_f32_e32 v52, v59, v52
	v_add_f32_e32 v52, v60, v52
	v_add_f32_e32 v123, v61, v52
	v_cvt_pk_bf16_f32 v48, v48, v49
	v_cvt_pk_bf16_f32 v52, v53, v54
	v_cvt_pk_bf16_f32 v49, v50, v51
	v_cvt_pk_bf16_f32 v53, v56, v57
	v_cvt_pk_bf16_f32 v54, v58, v59
	v_cvt_pk_bf16_f32 v51, v122, v55
	v_cvt_pk_bf16_f32 v55, v60, v61
	v_cvt_pk_bf16_f32 v50, v121, v120
	s_nop 0
	s_waitcnt lgkmcnt(6)
	v_mfma_f32_32x32x16_bf16 v[0:15], v[156:159], v[48:51], v[0:15]
	s_waitcnt lgkmcnt(4)
	v_mfma_f32_32x32x16_bf16 v[0:15], v[160:163], v[52:55], v[0:15]
	s_nop 0
	s_nop 0
	s_waitcnt lgkmcnt(2)
	v_mfma_f32_32x32x16_bf16 v[16:31], v[164:167], v[48:51], v[16:31]
	s_waitcnt lgkmcnt(0)
	v_mfma_f32_32x32x16_bf16 v[16:31], v[168:171], v[52:55], v[16:31]
	s_nop 0
	v_add_f32_e32 v107, v107, v123
	s_andn2_b64 vcc, exec, s[4:5]
	s_cbranch_vccnz .LBB0_1077

; #define LAS __attribute__((address_space(3)))
; __device__ __forceinline__ void attn_unit(int bh, int qb, const bf16_t* QKV, const bf16_t* KF, const float* cstab, const float* qg, bf16_t* MIX, LAS unsigned char* lds) {
;     ...
;         const float rs = __builtin_amdgcn_rsqf(ss * (1.0f / 96.0f) + EPS) * C2Q;
; #pragma unroll
;         for (int d0 = 0; d0 < 4; ++d0) { float v[8]; unpack8(raw[d0], v);
; #pragma unroll
;             for (int i = 0; i < 8; ++i) v[i] = v[i] * rs * qg[16 * d0 + 8 * hi + i];
;             qf[d0] = __builtin_bit_cast(bf16x8, pack8(v)); }
;         float x1[8], x2[8], o1[8], o2[8]; unpack8(raw[4], x1); unpack8(raw[5], x2);
; #pragma unroll
;         for (int i = 0; i < 8; ++i) { const float y1 = x1[i] * rs * qg[64 + 8 * hi + i], y2 = x2[i] * rs * qg[80 + 8 * hi + i], co = cs[i], si = cs[16 + i];
;             o1[i] = y1 * co - y2 * si; o2[i] = y1 * si + y2 * co; }
;         qf[4] = __builtin_bit_cast(bf16x8, pack8(o1)); qf[5] = __builtin_bit_cast(bf16x8, pack8(o2));
;     }
;     const char* Kg = (const char*)(KF + (size_t)bh * SEQ * 96);
;     const char* Vg = (const char*)(QKV + (size_t)b * SEQ * 1792 + 768 + h * 128 + 64) + (size_t)(tid >> 3) * 3584 + (tid & 7) * 16;
;     const int kofs0 = (tid / 12) * KROW + (tid % 12) * 16, kofs1 = ((tid + 512) / 12) * KROW + ((tid + 512) % 12) * 16, vofs = KBUF + (tid >> 3) * VROW + (tid & 7) * 16;
;     const int vtb = KBUF + (4 * hi + ((lane & 15) >> 2)) * VROW + (16 * ((lane >> 4) & 1) + 4 * (lane & 3)) * 2;
;     const int NT = 4 * (qb + 1);
;     u32x4 kr0, kr1 = {0u, 0u, 0u, 0u}, vr;
;     ...
;     float mrun = 0.f, lrun = 0.f;
;     f32x16 o0, o1, negm;
; #pragma unroll
;     for (int r = 0; r < 16; ++r) { o0[r] = 0.f; o1[r] = 0.f; negm[r] = 0.f; }
;     ATT_LOAD(0); ATT_WRITE(lds);
;     __syncthreads();
;     for (int t = 0; t < NT; ++t) {
;         LAS unsigned char* buf = lds + (t & 1) * BUFB;
;         if (t + 1 < NT) ATT_LOAD(t + 1);
; #pragma unroll
;         for (int kb = 0; kb < 2; ++kb) {
;             const int key0 = 64 * t + 32 * kb;
;             if (key0 > qw + 31) continue;
;             const LAS unsigned char* kp = buf + (32 * kb + r32) * KROW + 16 * hi;
;             f32x16 p = negm;
;             bf16x8 kfr[6];
; #pragma unroll
;             for (int d0 = 0; d0 < 6; ++d0) kfr[d0] = *(const LAS bf16x8*)(kp + 32 * d0);
;             __builtin_amdgcn_s_setprio(1);
; #pragma unroll
.LBB0_1084:
	s_or_b64 exec, exec, s[4:5]
	v_add_f32_e32 v74, v134, v146
	v_fmamk_f32 v74, v74, 0x3c2aaaab, v232
	v_rsq_f32_e32 v74, v74
	s_mov_b64 s[4:5], 0x680
	v_lshl_add_u64 v[136:137], v[136:137], 0, s[4:5]
	v_lshlrev_b32_e32 v105, 2, v144
	v_mul_f32_e32 v134, 0x3e16c740, v74
	v_pk_mul_f32 v[74:75], v[134:135], v[132:133] op_sel_hi:[0,1]
	v_pk_mul_f32 v[60:61], v[60:61], v[74:75]
	v_pk_mul_f32 v[74:75], v[134:135], v[128:129] op_sel_hi:[0,1]
	v_pk_mul_f32 v[76:77], v[134:135], v[130:131] op_sel_hi:[0,1]
	v_pk_mul_f32 v[56:57], v[56:57], v[74:75]
	v_pk_mul_f32 v[62:63], v[62:63], v[76:77]
	v_cvt_pk_bf16_f32 v76, v56, v57
	v_pk_mul_f32 v[56:57], v[134:135], v[88:89] op_sel_hi:[0,1]
	v_pk_mul_f32 v[52:53], v[56:57], v[52:53]
	v_pk_mul_f32 v[56:57], v[134:135], v[86:87] op_sel_hi:[0,1]
	v_pk_mul_f32 v[54:55], v[56:57], v[54:55]
	v_pk_mul_f32 v[56:57], v[134:135], v[80:81] op_sel_hi:[0,1]
	v_pk_mul_f32 v[48:49], v[56:57], v[48:49]
	v_pk_mul_f32 v[56:57], v[134:135], v[78:79] op_sel_hi:[0,1]
	v_cvt_pk_bf16_f32 v78, v52, v53
	v_add_co_u32_e32 v52, vcc, 0x38000, v136
	v_cvt_pk_bf16_f32 v80, v48, v49
	s_nop 0
	v_addc_co_u32_e32 v53, vcc, 0, v137, vcc
	global_load_dwordx4 v[86:89], v[52:53], off
	v_pk_mul_f32 v[48:49], v[134:135], v[124:125] op_sel_hi:[0,1]
	v_pk_mul_f32 v[44:45], v[48:49], v[44:45]
	v_pk_mul_f32 v[48:49], v[134:135], v[122:123] op_sel_hi:[0,1]
	v_pk_mul_f32 v[46:47], v[48:49], v[46:47]
	v_pk_mul_f32 v[48:49], v[134:135], v[84:85] op_sel_hi:[0,1]
	v_pk_mul_f32 v[40:41], v[48:49], v[40:41]
	v_pk_mul_f32 v[50:51], v[56:57], v[50:51]
	v_cvt_pk_bf16_f32 v84, v40, v41
	v_pk_mul_f32 v[40:41], v[134:135], v[120:121] op_sel_hi:[0,1]
	v_pk_mul_f32 v[36:37], v[40:41], v[36:37]
	v_pk_mul_f32 v[40:41], v[134:135], v[118:119] op_sel_hi:[0,1]
	v_pk_mul_f32 v[38:39], v[40:41], v[38:39]
	v_pk_mul_f32 v[40:41], v[134:135], v[92:93] op_sel_hi:[0,1]
	v_pk_mul_f32 v[32:33], v[40:41], v[32:33]
	v_cvt_pk_bf16_f32 v81, v50, v51
	v_cvt_pk_bf16_f32 v92, v32, v33
	v_pk_mul_f32 v[32:33], v[134:135], v[114:115] op_sel_hi:[0,1]
	v_pk_mul_f32 v[24:25], v[32:33], v[24:25]
	v_pk_mul_f32 v[32:33], v[134:135], v[116:117] op_sel_hi:[0,1]
	v_pk_mul_f32 v[20:21], v[32:33], v[20:21]
	v_pk_mul_f32 v[74:75], v[134:135], v[126:127] op_sel_hi:[0,1]
	v_pk_mul_f32 v[32:33], v[20:21], v[28:29]
	v_pk_mul_f32 v[48:49], v[134:135], v[82:83] op_sel_hi:[0,1]
	v_pk_fma_f32 v[32:33], v[24:25], v[16:17], v[32:33] neg_lo:[0,0,1] neg_hi:[0,0,1]
	v_pk_mul_f32 v[24:25], v[24:25], v[28:29]
	v_pk_mul_f32 v[40:41], v[134:135], v[90:91] op_sel_hi:[0,1]
	v_pk_fma_f32 v[16:17], v[20:21], v[16:17], v[24:25]
	v_pk_mul_f32 v[24:25], v[134:135], v[112:113] op_sel_hi:[0,1]
	v_pk_mul_f32 v[20:21], v[134:135], v[106:107] op_sel_hi:[0,1]
	v_pk_mul_f32 v[22:23], v[24:25], v[22:23]
	v_pk_mul_f32 v[20:21], v[20:21], v[26:27]
	v_pk_mul_f32 v[24:25], v[22:23], v[30:31]
	v_pk_mul_f32 v[58:59], v[58:59], v[74:75]
	v_pk_fma_f32 v[24:25], v[20:21], v[18:19], v[24:25] neg_lo:[0,0,1] neg_hi:[0,0,1]
	v_pk_mul_f32 v[20:21], v[20:21], v[30:31]
	v_pk_mul_f32 v[42:43], v[48:49], v[42:43]
	v_pk_fma_f32 v[18:19], v[22:23], v[18:19], v[20:21]
	v_pk_mul_f32 v[20:21], v[134:135], v[98:99] op_sel_hi:[0,1]
	v_pk_mul_f32 v[4:5], v[20:21], v[4:5]
	v_pk_mul_f32 v[20:21], v[134:135], v[100:101] op_sel_hi:[0,1]
	v_pk_mul_f32 v[8:9], v[20:21], v[8:9]
	v_pk_mul_f32 v[34:35], v[40:41], v[34:35]
	v_pk_mul_f32 v[20:21], v[8:9], v[12:13]
	v_mul_u32_u24_e32 v114, 0xd0, v138
	v_pk_fma_f32 v[20:21], v[4:5], v[0:1], v[20:21] neg_lo:[0,0,1] neg_hi:[0,0,1]
	v_pk_mul_f32 v[4:5], v[4:5], v[12:13]
	s_movk_i32 s2, 0xc0
	v_pk_fma_f32 v[0:1], v[8:9], v[0:1], v[4:5]
	v_pk_mul_f32 v[4:5], v[134:135], v[94:95] op_sel_hi:[0,1]
	v_pk_mul_f32 v[4:5], v[4:5], v[6:7]
	v_pk_mul_f32 v[6:7], v[134:135], v[96:97] op_sel_hi:[0,1]
	v_pk_mul_f32 v[6:7], v[6:7], v[10:11]
	v_cvt_pk_bf16_f32 v100, v0, v1
	v_lshrrev_b32_e32 v0, 2, v143
	v_pk_mul_f32 v[8:9], v[6:7], v[14:15]
	v_and_or_b32 v51, v0, 3, v105
	v_and_b32_e32 v0, 16, v143
	v_lshlrev_b32_e32 v1, 2, v143
	v_pk_fma_f32 v[8:9], v[4:5], v[2:3], v[8:9] neg_lo:[0,0,1] neg_hi:[0,0,1]
	v_pk_mul_f32 v[4:5], v[4:5], v[14:15]
	v_and_or_b32 v0, v1, 12, v0
	v_pk_fma_f32 v[2:3], v[6:7], v[2:3], v[4:5]
	v_lshlrev_b32_e32 v115, 1, v0
	v_add_u32_e32 v0, 0, v102
	v_cvt_pk_bf16_f32 v74, v60, v61
	v_cvt_pk_bf16_f32 v75, v62, v63
	v_cvt_pk_bf16_f32 v77, v58, v59
	v_cvt_pk_bf16_f32 v79, v54, v55
	v_cvt_pk_bf16_f32 v82, v44, v45
	v_cvt_pk_bf16_f32 v83, v46, v47
	v_cvt_pk_bf16_f32 v85, v42, v43
	v_cvt_pk_bf16_f32 v90, v36, v37
	v_cvt_pk_bf16_f32 v91, v38, v39
	v_cvt_pk_bf16_f32 v93, v34, v35
	v_cvt_pk_bf16_f32 v94, v32, v33
	v_cvt_pk_bf16_f32 v95, v24, v25
	v_cvt_pk_bf16_f32 v96, v20, v21
	v_cvt_pk_bf16_f32 v97, v8, v9
	v_cvt_pk_bf16_f32 v98, v16, v17
	v_cvt_pk_bf16_f32 v99, v18, v19
	v_cvt_pk_bf16_f32 v101, v2, v3
	v_mad_u32_u24 v119, v51, s2, 0
	s_cmp_lt_i32 s22, 0
	v_add_u32_e32 v50, v0, v114
	s_cbranch_scc1 .LBB0_1088
	ds_read_b128 v[0:3], v50
	ds_read_b128 v[16:19], v50 offset:32
	ds_read_b128 v[20:23], v50 offset:64
	ds_read_b128 v[24:27], v50 offset:96
	ds_read_b128 v[28:31], v50 offset:128
	ds_read_b128 v[32:35], v50 offset:160
	s_nop 0
	s_waitcnt lgkmcnt(5)
	v_mfma_f32_32x32x16_bf16 v[0:15], v[0:3], v[74:77], 0
	s_waitcnt lgkmcnt(4)
	v_mfma_f32_32x32x16_bf16 v[0:15], v[16:19], v[78:81], v[0:15]
	s_waitcnt lgkmcnt(3)
	v_mfma_f32_32x32x16_bf16 v[0:15], v[20:23], v[82:85], v[0:15]
	s_waitcnt lgkmcnt(2)
	v_mfma_f32_32x32x16_bf16 v[0:15], v[24:27], v[90:93], v[0:15]
	s_waitcnt lgkmcnt(1)
	v_mfma_f32_32x32x16_bf16 v[0:15], v[28:31], v[94:97], v[0:15]
	s_waitcnt lgkmcnt(0)
	v_mfma_f32_32x32x16_bf16 v[0:15], v[32:35], v[98:101], v[0:15]
	s_nop 0
	s_cmp_lg_u32 s22, 0
	s_cbranch_scc1 .LBB0_1087
; __device__ __forceinline__ void attn_unit(int bh, int qb, const bf16_t* QKV, const bf16_t* KF, const float* cstab, const float* qg, bf16_t* MIX, LAS unsigned char* lds) {
;     ...
;             if (key0 + 31 > qw) {
; #pragma unroll
;                 for (int r = 0; r < 16; ++r) { const int key = key0 + (r & 3) + 8 * (r >> 2) + 4 * hi; if (key > q) p[r] = -1e30f; }
;             }
;             float mx = fmaxf(fmaxf(p[0], p[1]), fmaxf(p[2], p[3]));
; #pragma unroll
;             for (int r = 4; r < 16; r += 4) mx = fmaxf(mx, fmaxf(fmaxf(p[r], p[r + 1]), fmaxf(p[r + 2], p[r + 3])));
;             mx = pg8::max32(mx);
;             if (key0 == 0 || __any(mx > 4.0f)) {
;                 const float dl = (key0 == 0) ? mx : fmaxf(mx, 0.f), f = __builtin_amdgcn_exp2f(-dl);
;                 mrun += dl; lrun *= f;
; #pragma unroll
;                 for (int r = 0; r < 16; ++r) { o0[r] *= f; o1[r] *= f; p[r] -= dl; negm[r] = -mrun; }
;             }
;             float ps = 0.f;
; #pragma unroll
;             for (int r = 0; r < 16; ++r) { p[r] = __builtin_amdgcn_exp2f(p[r]); ps += p[r]; }
;             lrun += ps;
;             u32x4 w0, w1;
; #pragma unroll
;             for (int k = 0; k < 4; ++k) { w0[k] = cvt_pk_bf16(p[2 * k], p[2 * k + 1]); w1[k] = cvt_pk_bf16(p[8 + 2 * k], p[8 + 2 * k + 1]); }
;             const bf16x8 pb0 = __builtin_bit_cast(bf16x8, w0), pb1 = __builtin_bit_cast(bf16x8, w1);
;             const LAS unsigned char* vp = buf + vtb + (32 * kb) * VROW;
; #pragma unroll
;             for (int db = 0; db < 2; ++db) {
;                 const v4i16_t a0 = __builtin_amdgcn_ds_read_tr16_b64_v4i16((LAS v4i16_t*)(vp + db * 64));
;                 const v4i16_t a1 = __builtin_amdgcn_ds_read_tr16_b64_v4i16((LAS v4i16_t*)(vp + db * 64 + 8 * VROW));
;                 const v4i16_t c0 = __builtin_amdgcn_ds_read_tr16_b64_v4i16((LAS v4i16_t*)(vp + db * 64 + 16 * VROW));
;                 const v4i16_t c1 = __builtin_amdgcn_ds_read_tr16_b64_v4i16((LAS v4i16_t*)(vp + db * 64 + 24 * VROW));
;                 const bf16x8 va = {a0[0], a0[1], a0[2], a0[3], a1[0], a1[1], a1[2], a1[3]}, vc = {c0[0], c0[1], c0[2], c0[3], c1[0], c1[1], c1[2], c1[3]};
;                 __builtin_amdgcn_s_setprio(1);
;                 if (db == 0) { o0 = MFMA32(va, pb0, o0); o0 = MFMA32(vc, pb1, o0); }
;                 else { o1 = MFMA32(va, pb0, o1); o1 = MFMA32(vc, pb1, o1); }
	v_cmp_lt_i32_e32 vcc, v105, v139
	v_or_b32_e32 v16, 2, v105
	v_or_b32_e32 v17, 3, v105
	s_nop 5
	v_cndmask_b32_e32 v1, v239, v1, vcc
	v_cmp_le_i32_e32 vcc, v105, v139
	v_or_b32_e32 v18, 8, v105
	v_or_b32_e32 v19, 9, v105
	v_cndmask_b32_e32 v0, v239, v0, vcc
	v_cmp_le_i32_e32 vcc, v16, v139
	v_or_b32_e32 v20, 10, v105
	v_or_b32_e32 v21, 11, v105
	v_cndmask_b32_e32 v2, v239, v2, vcc
	v_cmp_le_i32_e32 vcc, v17, v139
	v_or_b32_e32 v22, 16, v105
	v_or_b32_e32 v23, 17, v105
	v_cndmask_b32_e32 v3, v239, v3, vcc
	v_cmp_le_i32_e32 vcc, v18, v139
	v_or_b32_e32 v24, 18, v105
	v_or_b32_e32 v25, 19, v105
	v_cndmask_b32_e32 v4, v239, v4, vcc
	v_cmp_le_i32_e32 vcc, v19, v139
	v_or_b32_e32 v26, 24, v105
	v_or_b32_e32 v27, 25, v105
	v_cndmask_b32_e32 v5, v239, v5, vcc
	v_cmp_le_i32_e32 vcc, v20, v139
	v_or_b32_e32 v28, 26, v105
	v_or_b32_e32 v29, 27, v105
	v_cndmask_b32_e32 v6, v239, v6, vcc
	v_cmp_le_i32_e32 vcc, v21, v139
	s_nop 1
	v_cndmask_b32_e32 v7, v239, v7, vcc
	v_cmp_le_i32_e32 vcc, v22, v139
	s_nop 1
	v_cndmask_b32_e32 v8, v239, v8, vcc
	v_cmp_le_i32_e32 vcc, v23, v139
	s_nop 1
	v_cndmask_b32_e32 v9, v239, v9, vcc
	v_cmp_le_i32_e32 vcc, v24, v139
	s_nop 1
	v_cndmask_b32_e32 v10, v239, v10, vcc
	v_cmp_le_i32_e32 vcc, v25, v139
	s_nop 1
	v_cndmask_b32_e32 v11, v239, v11, vcc
	v_cmp_le_i32_e32 vcc, v26, v139
	s_nop 1
	v_cndmask_b32_e32 v12, v239, v12, vcc
	v_cmp_le_i32_e32 vcc, v27, v139
	s_nop 1
	v_cndmask_b32_e32 v13, v239, v13, vcc
	v_cmp_le_i32_e32 vcc, v28, v139
	s_nop 1
	v_cndmask_b32_e32 v14, v239, v14, vcc
	v_cmp_le_i32_e32 vcc, v29, v139
	s_nop 1
	v_cndmask_b32_e32 v15, v239, v15, vcc
.LBB0_1087:
	s_nop 8
	v_max3_f32 v16, v0, v1, v2
	v_max3_f32 v17, v3, v4, v5
	v_max3_f32 v18, v6, v7, v8
	v_max3_f32 v19, v9, v10, v11
	v_max3_f32 v16, v16, v17, v18
	v_max3_f32 v17, v12, v13, v14
	v_max3_f32 v16, v16, v19, v17
	v_max_f32_e32 v16, v16, v15
	v_mov_b32_e32 v17, v16
	s_nop 1
	v_permlane32_swap_b32_e32 v16, v17
	v_max_f32_e32 v48, v16, v17
	v_sub_f32_e32 v0, v0, v48
	v_sub_f32_e32 v1, v1, v48
	v_exp_f32_e64 v16, -v48
	v_exp_f32_e32 v0, v0
	v_sub_f32_e32 v2, v2, v48
	v_exp_f32_e32 v1, v1
	v_sub_f32_e32 v3, v3, v48
	v_exp_f32_e32 v2, v2
	v_sub_f32_e32 v4, v4, v48
	v_exp_f32_e32 v3, v3
	v_sub_f32_e32 v5, v5, v48
	v_mul_f32_e32 v32, 0, v16
	v_exp_f32_e32 v4, v4
	v_sub_f32_e32 v6, v6, v48
	v_add_f32_e32 v16, v1, v0
	v_exp_f32_e32 v5, v5
	v_sub_f32_e32 v7, v7, v48
	v_add_f32_e32 v16, v2, v16
	v_exp_f32_e32 v6, v6
	v_sub_f32_e32 v8, v8, v48
	v_add_f32_e32 v16, v3, v16
	v_exp_f32_e32 v7, v7
	v_sub_f32_e32 v9, v9, v48
	v_add_f32_e32 v16, v4, v16
	v_exp_f32_e32 v8, v8
	v_sub_f32_e32 v10, v10, v48
	v_add_f32_e32 v16, v5, v16
	v_exp_f32_e32 v9, v9
	v_sub_f32_e32 v11, v11, v48
	v_add_f32_e32 v16, v6, v16
	v_exp_f32_e32 v10, v10
	v_sub_f32_e32 v12, v12, v48
	v_add_f32_e32 v16, v7, v16
	v_exp_f32_e32 v11, v11
	v_sub_f32_e32 v13, v13, v48
	v_add_f32_e32 v16, v8, v16
	v_exp_f32_e32 v12, v12
	v_sub_f32_e32 v14, v14, v48
	v_add_f32_e32 v16, v9, v16
	v_exp_f32_e32 v13, v13
	v_sub_f32_e32 v15, v15, v48
	v_add_f32_e32 v16, v10, v16
	v_exp_f32_e32 v14, v14
	v_add_f32_e32 v16, v11, v16
	v_exp_f32_e32 v15, v15
	v_add_f32_e32 v16, v12, v16
	v_add_f32_e32 v16, v13, v16
	v_add_f32_e32 v16, v14, v16
	v_add_u32_e32 v24, v119, v115
	v_add_f32_e32 v107, v15, v16
	ds_read_b64_tr_b16 v[16:17], v24 offset:13312
	ds_read_b64_tr_b16 v[18:19], v24 offset:14848
	ds_read_b64_tr_b16 v[20:21], v24 offset:16384
	ds_read_b64_tr_b16 v[22:23], v24 offset:17920
	s_movk_i32 s60, 0xc0
	v_mov_b32_e32 v33, v32
	v_mov_b32_e32 v34, v32
	v_mov_b32_e32 v35, v32
	v_mov_b32_e32 v36, v32
	v_mov_b32_e32 v37, v32
	v_mov_b32_e32 v38, v32
	v_mov_b32_e32 v39, v32
	v_mov_b32_e32 v40, v32
	v_mov_b32_e32 v41, v32
	v_mov_b32_e32 v42, v32
	v_mov_b32_e32 v43, v32
	v_mov_b32_e32 v44, v32
	v_mov_b32_e32 v45, v32
	v_mov_b32_e32 v46, v32
	v_mov_b32_e32 v47, v32
	v_cvt_pk_bf16_f32 v52, v0, v1
	v_cvt_pk_bf16_f32 v56, v8, v9
	v_cvt_pk_bf16_f32 v53, v2, v3
	v_cvt_pk_bf16_f32 v57, v10, v11
	v_cvt_pk_bf16_f32 v54, v4, v5
	v_cvt_pk_bf16_f32 v58, v12, v13
	v_cvt_pk_bf16_f32 v55, v6, v7
	v_cvt_pk_bf16_f32 v59, v14, v15
	s_nop 0
	s_waitcnt lgkmcnt(2)
	v_mfma_f32_32x32x16_bf16 v[0:15], v[16:19], v[52:55], v[32:47]
	s_waitcnt lgkmcnt(0)
	v_mfma_f32_32x32x16_bf16 v[0:15], v[20:23], v[56:59], v[0:15]
	s_nop 0
	ds_read_b64_tr_b16 v[60:61], v24 offset:13376
	ds_read_b64_tr_b16 v[62:63], v24 offset:14912
	ds_read_b64_tr_b16 v[120:121], v24 offset:16448
	ds_read_b64_tr_b16 v[122:123], v24 offset:17984
	s_nop 0
	v_mov_b64_e32 v[16:17], v[32:33]
	v_mov_b64_e32 v[18:19], v[34:35]
	v_mov_b64_e32 v[20:21], v[36:37]
	v_mov_b64_e32 v[22:23], v[38:39]
	v_mov_b64_e32 v[24:25], v[40:41]
	v_mov_b64_e32 v[26:27], v[42:43]
	v_mov_b64_e32 v[28:29], v[44:45]
	v_mov_b64_e32 v[30:31], v[46:47]
	s_waitcnt lgkmcnt(2)
	s_nop 0
	v_mfma_f32_32x32x16_bf16 v[16:31], v[60:63], v[52:55], v[16:31]
	s_waitcnt lgkmcnt(0)
	v_mfma_f32_32x32x16_bf16 v[16:31], v[120:123], v[56:59], v[16:31]
	s_nop 0
	v_mov_b32_e32 v49, v32
	v_mov_b32_e32 v106, v65
	v_add_f32_e64 v106, v48, v106
	v_add_f32_e64 v107, v49, v107
	v_xor_b32_e32 v32, 0x80000000, v106
	v_mov_b32_e32 v33, v32
	v_mov_b32_e32 v34, v32
	v_mov_b32_e32 v35, v32
	v_mov_b32_e32 v36, v32
	v_mov_b32_e32 v37, v32
	v_mov_b32_e32 v38, v32
	v_mov_b32_e32 v39, v32
	v_mov_b32_e32 v40, v32
	v_mov_b32_e32 v41, v32
	v_mov_b32_e32 v42, v32
	v_mov_b32_e32 v43, v32
	v_mov_b32_e32 v44, v32
	v_mov_b32_e32 v45, v32
	v_mov_b32_e32 v46, v32
	v_mov_b32_e32 v47, v32
	s_branch .LBB0_1089

; #define LAS __attribute__((address_space(3)))
; #define MFMA32(a, b, c) __builtin_amdgcn_mfma_f32_32x32x16_bf16(a, b, c, 0, 0, 0)
; __device__ __forceinline__ void attn_unit(int bh, int qb, const bf16_t* QKV, const bf16_t* KF, const float* cstab, const float* qg, bf16_t* MIX, LAS unsigned char* lds) {
;     ...
;         for (int kb = 0; kb < 2; ++kb) {
;             const int key0 = 64 * t + 32 * kb;
;             if (key0 > qw + 31) continue;
;             const LAS unsigned char* kp = buf + (32 * kb + r32) * KROW + 16 * hi;
;             f32x16 p = negm;
;             bf16x8 kfr[6];
; #pragma unroll
;             for (int d0 = 0; d0 < 6; ++d0) kfr[d0] = *(const LAS bf16x8*)(kp + 32 * d0);
;             __builtin_amdgcn_s_setprio(1);
; #pragma unroll
;             for (int d0 = 0; d0 < 6; ++d0) p = MFMA32(kfr[d0], qf[d0], p);
;             __builtin_amdgcn_s_setprio(0);
;             if (key0 + 31 > qw) {
; #pragma unroll
;                 for (int r = 0; r < 16; ++r) { const int key = key0 + (r & 3) + 8 * (r >> 2) + 4 * hi; if (key > q) p[r] = -1e30f; }
.LBB0_1089:
	s_lshl_b32 s2, s36, 6
	s_or_b32 s18, s22, 31
	v_and_b32_e32 v116, 63, v143
	v_lshlrev_b32_e32 v117, 3, v144
	v_mad_i64_i32 v[112:113], s[4:5], v145, s85, 0
	v_mul_u32_u24_e32 v118, 0xc0, v51
	s_cmp_lt_i32 s18, 32
	s_cbranch_scc1 .LBB0_1095
	ds_read_b128 v[120:123], v50 offset:6656
	ds_read_b128 v[124:127], v50 offset:6688
	ds_read_b128 v[128:131], v50 offset:6720
	ds_read_b128 v[144:147], v50 offset:6752
	ds_read_b128 v[148:151], v50 offset:6784
	ds_read_b128 v[152:155], v50 offset:6816
	s_nop 0
	s_waitcnt lgkmcnt(5)
	v_mfma_f32_32x32x16_bf16 v[48:63], v[120:123], v[74:77], v[32:47]
	s_waitcnt lgkmcnt(4)
	v_mfma_f32_32x32x16_bf16 v[48:63], v[124:127], v[78:81], v[48:63]
	s_waitcnt lgkmcnt(3)
	v_mfma_f32_32x32x16_bf16 v[48:63], v[128:131], v[82:85], v[48:63]
	s_waitcnt lgkmcnt(2)
	v_mfma_f32_32x32x16_bf16 v[48:63], v[144:147], v[90:93], v[48:63]
	s_waitcnt lgkmcnt(1)
	v_mfma_f32_32x32x16_bf16 v[48:63], v[148:151], v[94:97], v[48:63]
	s_waitcnt lgkmcnt(0)
	v_mfma_f32_32x32x16_bf16 v[48:63], v[152:155], v[98:101], v[48:63]
	s_nop 0
	s_cmp_gt_u32 s22, 62
	s_cbranch_scc1 .LBB0_1092
	v_or_b32_e32 v120, 32, v105
	v_cmp_lt_i32_e32 vcc, v120, v139
	s_nop 6
	v_cndmask_b32_e32 v49, v239, v49, vcc
	v_cmp_le_i32_e32 vcc, v120, v139
	v_or_b32_e32 v120, 34, v105
	s_nop 0
	v_cndmask_b32_e32 v48, v239, v48, vcc
	v_cmp_le_i32_e32 vcc, v120, v139
	v_or_b32_e32 v120, 35, v105
	s_nop 0
	v_cndmask_b32_e32 v50, v239, v50, vcc
	v_cmp_le_i32_e32 vcc, v120, v139
	v_or_b32_e32 v120, 40, v105
	s_nop 0
	v_cndmask_b32_e32 v51, v239, v51, vcc
	v_cmp_le_i32_e32 vcc, v120, v139
	v_or_b32_e32 v120, 41, v105
	s_nop 0
	v_cndmask_b32_e32 v52, v239, v52, vcc
	v_cmp_le_i32_e32 vcc, v120, v139
	v_or_b32_e32 v120, 42, v105
	s_nop 0
	v_cndmask_b32_e32 v53, v239, v53, vcc
	v_cmp_le_i32_e32 vcc, v120, v139
	v_or_b32_e32 v120, 43, v105
	s_nop 0
	v_cndmask_b32_e32 v54, v239, v54, vcc
	v_cmp_le_i32_e32 vcc, v120, v139
	v_or_b32_e32 v120, 48, v105
	s_nop 0
	v_cndmask_b32_e32 v55, v239, v55, vcc
	v_cmp_le_i32_e32 vcc, v120, v139
	v_or_b32_e32 v120, 49, v105
	s_nop 0
	v_cndmask_b32_e32 v56, v239, v56, vcc
	v_cmp_le_i32_e32 vcc, v120, v139
	v_or_b32_e32 v120, 50, v105
	s_nop 0
	v_cndmask_b32_e32 v57, v239, v57, vcc
	v_cmp_le_i32_e32 vcc, v120, v139
	v_or_b32_e32 v120, 51, v105
	s_nop 0
	v_cndmask_b32_e32 v58, v239, v58, vcc
	v_cmp_le_i32_e32 vcc, v120, v139
	v_or_b32_e32 v120, 56, v105
	s_nop 0
	v_cndmask_b32_e32 v59, v239, v59, vcc
	v_cmp_le_i32_e32 vcc, v120, v139
	v_or_b32_e32 v120, 57, v105
	s_nop 0
	v_cndmask_b32_e32 v60, v239, v60, vcc
	v_cmp_le_i32_e32 vcc, v120, v139
	v_or_b32_e32 v120, 58, v105
	s_nop 0
	v_cndmask_b32_e32 v61, v239, v61, vcc
	v_cmp_le_i32_e32 vcc, v120, v139
	v_or_b32_e32 v120, 59, v105
	s_nop 0
	v_cndmask_b32_e32 v62, v239, v62, vcc
	v_cmp_le_i32_e32 vcc, v120, v139
	s_nop 1
	v_cndmask_b32_e32 v63, v239, v63, vcc

; #define LAS __attribute__((address_space(3)))
; #define MFMA32(a, b, c) __builtin_amdgcn_mfma_f32_32x32x16_bf16(a, b, c, 0, 0, 0)
; #define ATT_LOAD(t) do { kr0 = *(const u32x4*)(Kg + (size_t)(t) * 12288 + tid * 16); if (tid < 256) kr1 = *(const u32x4*)(Kg + (size_t)(t) * 12288 + (tid + 512) * 16); vr = *(const u32x4*)(Vg + (size_t)(t) * (64 * 3584)); } while (0)
; __device__ __forceinline__ void attn_unit(int bh, int qb, const bf16_t* QKV, const bf16_t* KF, const float* cstab, const float* qg, bf16_t* MIX, LAS unsigned char* lds) {
;     ...
;         LAS unsigned char* buf = lds + (t & 1) * BUFB;
;         if (t + 1 < NT) ATT_LOAD(t + 1);
; #pragma unroll
;         for (int kb = 0; kb < 2; ++kb) {
;             const int key0 = 64 * t + 32 * kb;
;             if (key0 > qw + 31) continue;
;             const LAS unsigned char* kp = buf + (32 * kb + r32) * KROW + 16 * hi;
;             f32x16 p = negm;
;             bf16x8 kfr[6];
; #pragma unroll
;             for (int d0 = 0; d0 < 6; ++d0) kfr[d0] = *(const LAS bf16x8*)(kp + 32 * d0);
;             __builtin_amdgcn_s_setprio(1);
; #pragma unroll
;             for (int d0 = 0; d0 < 6; ++d0) p = MFMA32(kfr[d0], qf[d0], p);
;             __builtin_amdgcn_s_setprio(0);
;             if (key0 + 31 > qw) {
; #pragma unroll
;                 for (int r = 0; r < 16; ++r) { const int key = key0 + (r & 3) + 8 * (r >> 2) + 4 * hi; if (key > q) p[r] = -1e30f; }
.LBB0_1102:
	s_and_b32 s15, 1, s19
	s_cselect_b32 s14, 0, 0x6400
	s_add_i32 s30, s14, 0
	s_add_i32 s14, s29, 64
	v_add_u32_e32 v48, s30, v102
	v_add_u32_e32 v119, s30, v118
	s_cmp_gt_i32 s14, s18
	v_add_u32_e32 v120, v48, v114
	s_cbranch_scc1 .LBB0_1109
	ds_read_b128 v[122:125], v120
	ds_read_b128 v[126:129], v120 offset:32
	ds_read_b128 v[130:133], v120 offset:64
	ds_read_b128 v[140:143], v120 offset:96
	ds_read_b128 v[144:147], v120 offset:128
	ds_read_b128 v[148:151], v120 offset:160
	s_nop 0
	s_waitcnt lgkmcnt(5)
	v_mfma_f32_32x32x16_bf16 v[48:63], v[122:125], v[74:77], v[32:47]
	s_waitcnt lgkmcnt(4)
	v_mfma_f32_32x32x16_bf16 v[48:63], v[126:129], v[78:81], v[48:63]
	s_waitcnt lgkmcnt(3)
	v_mfma_f32_32x32x16_bf16 v[48:63], v[130:133], v[82:85], v[48:63]
	s_waitcnt lgkmcnt(2)
	v_mfma_f32_32x32x16_bf16 v[48:63], v[140:143], v[90:93], v[48:63]
	s_waitcnt lgkmcnt(1)
	v_mfma_f32_32x32x16_bf16 v[48:63], v[144:147], v[94:97], v[48:63]
	s_waitcnt lgkmcnt(0)
	v_mfma_f32_32x32x16_bf16 v[48:63], v[148:151], v[98:101], v[48:63]
	v_add_u32_e32 v172, v119, v115
	ds_read_b64_tr_b16 v[156:157], v172 offset:13312
	ds_read_b64_tr_b16 v[158:159], v172 offset:14848
	ds_read_b64_tr_b16 v[160:161], v172 offset:16384
	ds_read_b64_tr_b16 v[162:163], v172 offset:17920
	ds_read_b64_tr_b16 v[164:165], v172 offset:13376
	ds_read_b64_tr_b16 v[166:167], v172 offset:14912
	ds_read_b64_tr_b16 v[168:169], v172 offset:16448
	ds_read_b64_tr_b16 v[170:171], v172 offset:17984
	ds_read_b128 v[202:205], v120 offset:6656
	ds_read_b128 v[206:209], v120 offset:6688
	ds_read_b128 v[210:213], v120 offset:6720
	ds_read_b128 v[214:217], v120 offset:6752
	ds_read_b128 v[218:221], v120 offset:6784
	ds_read_b128 v[222:225], v120 offset:6816
	s_nop 0
	s_add_i32 s30, s29, 0x5f
	s_cmp_le_i32 s30, s22
	s_cbranch_scc1 .LBB0_1105
	v_add_u32_e32 v121, s29, v105
	v_add_u32_e32 v122, 64, v121
	v_cmp_lt_i32_e32 vcc, v122, v139
	s_nop 4
	v_cndmask_b32_e32 v49, v239, v49, vcc
	v_cmp_le_i32_e32 vcc, v122, v139
	v_add_u32_e32 v122, 0x42, v121
	s_nop 0
	v_cndmask_b32_e32 v48, v239, v48, vcc
	v_cmp_le_i32_e32 vcc, v122, v139
	v_add_u32_e32 v122, 0x43, v121
	s_nop 0
	v_cndmask_b32_e32 v50, v239, v50, vcc
	v_cmp_le_i32_e32 vcc, v122, v139
	v_add_u32_e32 v122, 0x48, v121
	s_nop 0
	v_cndmask_b32_e32 v51, v239, v51, vcc
	v_cmp_le_i32_e32 vcc, v122, v139
	v_add_u32_e32 v122, 0x49, v121
	s_nop 0
	v_cndmask_b32_e32 v52, v239, v52, vcc
	v_cmp_le_i32_e32 vcc, v122, v139
	v_add_u32_e32 v122, 0x4a, v121
	s_nop 0
	v_cndmask_b32_e32 v53, v239, v53, vcc
	v_cmp_le_i32_e32 vcc, v122, v139
	v_add_u32_e32 v122, 0x4b, v121
	s_nop 0
	v_cndmask_b32_e32 v54, v239, v54, vcc
	v_cmp_le_i32_e32 vcc, v122, v139
	v_add_u32_e32 v122, 0x50, v121
	s_nop 0
	v_cndmask_b32_e32 v55, v239, v55, vcc
	v_cmp_le_i32_e32 vcc, v122, v139
	v_add_u32_e32 v122, 0x51, v121
	s_nop 0
	v_cndmask_b32_e32 v56, v239, v56, vcc
	v_cmp_le_i32_e32 vcc, v122, v139
	v_add_u32_e32 v122, 0x52, v121
	s_nop 0
	v_cndmask_b32_e32 v57, v239, v57, vcc
	v_cmp_le_i32_e32 vcc, v122, v139
	v_add_u32_e32 v122, 0x53, v121
	s_nop 0
	v_cndmask_b32_e32 v58, v239, v58, vcc
	v_cmp_le_i32_e32 vcc, v122, v139
	v_add_u32_e32 v122, 0x58, v121
	s_nop 0
	v_cndmask_b32_e32 v59, v239, v59, vcc
	v_cmp_le_i32_e32 vcc, v122, v139
	v_add_u32_e32 v122, 0x59, v121
	s_nop 0
	v_cndmask_b32_e32 v60, v239, v60, vcc
	v_cmp_le_i32_e32 vcc, v122, v139
	v_add_u32_e32 v122, 0x5a, v121
	v_add_u32_e32 v121, 0x5b, v121
	v_cndmask_b32_e32 v61, v239, v61, vcc
	v_cmp_le_i32_e32 vcc, v122, v139
	s_nop 1
	v_cndmask_b32_e32 v62, v239, v62, vcc
	v_cmp_le_i32_e32 vcc, v121, v139
	s_nop 1
	v_cndmask_b32_e32 v63, v239, v63, vcc

; __device__ __forceinline__ unsigned cvt_pk_bf16(float lo, float hi) { const f32x2c_ v = {lo, hi}; const bf16x2c_ b = __builtin_convertvector(v, bf16x2c_); return __builtin_bit_cast(unsigned, b); }
; #define LAS __attribute__((address_space(3)))
; #define MFMA32(a, b, c) __builtin_amdgcn_mfma_f32_32x32x16_bf16(a, b, c, 0, 0, 0)
; __device__ __forceinline__ void attn_unit(int bh, int qb, const bf16_t* QKV, const bf16_t* KF, const float* cstab, const float* qg, bf16_t* MIX, LAS unsigned char* lds) {
;     ...
;             float ps = 0.f;
; #pragma unroll
;             for (int r = 0; r < 16; ++r) { p[r] = __builtin_amdgcn_exp2f(p[r]); ps += p[r]; }
;             lrun += ps;
;             u32x4 w0, w1;
; #pragma unroll
;             for (int k = 0; k < 4; ++k) { w0[k] = cvt_pk_bf16(p[2 * k], p[2 * k + 1]); w1[k] = cvt_pk_bf16(p[8 + 2 * k], p[8 + 2 * k + 1]); }
;             const bf16x8 pb0 = __builtin_bit_cast(bf16x8, w0), pb1 = __builtin_bit_cast(bf16x8, w1);
;             const LAS unsigned char* vp = buf + vtb + (32 * kb) * VROW;
; #pragma unroll
;             for (int db = 0; db < 2; ++db) {
;                 const v4i16_t a0 = __builtin_amdgcn_ds_read_tr16_b64_v4i16((LAS v4i16_t*)(vp + db * 64));
;                 const v4i16_t a1 = __builtin_amdgcn_ds_read_tr16_b64_v4i16((LAS v4i16_t*)(vp + db * 64 + 8 * VROW));
;                 const v4i16_t c0 = __builtin_amdgcn_ds_read_tr16_b64_v4i16((LAS v4i16_t*)(vp + db * 64 + 16 * VROW));
;                 const v4i16_t c1 = __builtin_amdgcn_ds_read_tr16_b64_v4i16((LAS v4i16_t*)(vp + db * 64 + 24 * VROW));
;                 const bf16x8 va = {a0[0], a0[1], a0[2], a0[3], a1[0], a1[1], a1[2], a1[3]}, vc = {c0[0], c0[1], c0[2], c0[3], c1[0], c1[1], c1[2], c1[3]};
;                 __builtin_amdgcn_s_setprio(1);
;                 if (db == 0) { o0 = MFMA32(va, pb0, o0); o0 = MFMA32(vc, pb1, o0); }
;                 else { o1 = MFMA32(va, pb0, o1); o1 = MFMA32(vc, pb1, o1); }
;                 __builtin_amdgcn_s_setprio(0);
;             }
.LBB0_1107:
	v_exp_f32_e32 v48, v48
	v_exp_f32_e32 v49, v49
	v_exp_f32_e32 v50, v50
	v_exp_f32_e32 v51, v51
	v_exp_f32_e32 v122, v52
	v_add_f32_e32 v121, v49, v48
	v_add_f32_e32 v121, v50, v121
	v_add_f32_e32 v121, v51, v121
	v_add_f32_e32 v52, v122, v121
	v_exp_f32_e32 v121, v53
	v_exp_f32_e32 v123, v54
	v_exp_f32_e32 v55, v55
	v_exp_f32_e32 v53, v56
	v_add_f32_e32 v52, v121, v52
	v_exp_f32_e32 v54, v57
	v_add_f32_e32 v52, v123, v52
	v_exp_f32_e32 v56, v58
	v_add_f32_e32 v52, v55, v52
	v_exp_f32_e32 v57, v59
	v_add_f32_e32 v52, v53, v52
	v_exp_f32_e32 v58, v60
	v_add_f32_e32 v52, v54, v52
	v_exp_f32_e32 v59, v61
	v_add_f32_e32 v52, v56, v52
	v_exp_f32_e32 v60, v62
	v_add_f32_e32 v52, v57, v52
	v_exp_f32_e32 v61, v63
	v_add_f32_e32 v52, v58, v52
	v_add_f32_e32 v52, v59, v52
	v_add_f32_e32 v52, v60, v52
	v_cvt_pk_bf16_f32 v48, v48, v49
	v_cvt_pk_bf16_f32 v49, v50, v51
	v_cvt_pk_bf16_f32 v50, v122, v121
	v_add_f32_e32 v124, v61, v52
	v_cvt_pk_bf16_f32 v52, v53, v54
	v_cvt_pk_bf16_f32 v53, v56, v57
	v_cvt_pk_bf16_f32 v54, v58, v59
	v_cvt_pk_bf16_f32 v51, v123, v55
	v_cvt_pk_bf16_f32 v55, v60, v61
	s_nop 0
	s_waitcnt lgkmcnt(12)
	v_mfma_f32_32x32x16_bf16 v[0:15], v[156:159], v[48:51], v[0:15]
	s_waitcnt lgkmcnt(10)
	v_mfma_f32_32x32x16_bf16 v[0:15], v[160:163], v[52:55], v[0:15]
	s_nop 0
	s_nop 0
	s_waitcnt lgkmcnt(8)
	v_mfma_f32_32x32x16_bf16 v[16:31], v[164:167], v[48:51], v[16:31]
	s_waitcnt lgkmcnt(6)
	v_mfma_f32_32x32x16_bf16 v[16:31], v[168:171], v[52:55], v[16:31]
	s_nop 0
	v_add_f32_e32 v107, v107, v124
	s_add_i32 s30, s29, 0x60
	s_cmp_gt_i32 s30, s18
	s_cbranch_scc0 .LBB0_1110

; __device__ __forceinline__ void attn_unit(int bh, int qb, const bf16_t* QKV, const bf16_t* KF, const float* cstab, const float* qg, bf16_t* MIX, LAS unsigned char* lds) {
;     ...
;             if (key0 > qw + 31) continue;
;             const LAS unsigned char* kp = buf + (32 * kb + r32) * KROW + 16 * hi;
;             f32x16 p = negm;
;             bf16x8 kfr[6];
; #pragma unroll
;             for (int d0 = 0; d0 < 6; ++d0) kfr[d0] = *(const LAS bf16x8*)(kp + 32 * d0);
;             __builtin_amdgcn_s_setprio(1);
; #pragma unroll
;             for (int d0 = 0; d0 < 6; ++d0) p = MFMA32(kfr[d0], qf[d0], p);
;             __builtin_amdgcn_s_setprio(0);
;             if (key0 + 31 > qw) {
; #pragma unroll
;                 for (int r = 0; r < 16; ++r) { const int key = key0 + (r & 3) + 8 * (r >> 2) + 4 * hi; if (key > q) p[r] = -1e30f; }
;             }
;             float mx = fmaxf(fmaxf(p[0], p[1]), fmaxf(p[2], p[3]));
; #pragma unroll
;             for (int r = 4; r < 16; r += 4) mx = fmaxf(mx, fmaxf(fmaxf(p[r], p[r + 1]), fmaxf(p[r + 2], p[r + 3])));
;             mx = pg8::max32(mx);
;             if (key0 == 0 || __any(mx > 4.0f)) {
;                 const float dl = (key0 == 0) ? mx : fmaxf(mx, 0.f), f = __builtin_amdgcn_exp2f(-dl);
;                 mrun += dl; lrun *= f;
; #pragma unroll
;                 for (int r = 0; r < 16; ++r) { o0[r] *= f; o1[r] *= f; p[r] -= dl; negm[r] = -mrun; }
;             }
;             float ps = 0.f;
; #pragma unroll
;             for (int r = 0; r < 16; ++r) { p[r] = __builtin_amdgcn_exp2f(p[r]); ps += p[r]; }
;             lrun += ps;
;             u32x4 w0, w1;
; #pragma unroll
;             for (int k = 0; k < 4; ++k) { w0[k] = cvt_pk_bf16(p[2 * k], p[2 * k + 1]); w1[k] = cvt_pk_bf16(p[8 + 2 * k], p[8 + 2 * k + 1]); }
;             const bf16x8 pb0 = __builtin_bit_cast(bf16x8, w0), pb1 = __builtin_bit_cast(bf16x8, w1);
;             const LAS unsigned char* vp = buf + vtb + (32 * kb) * VROW;
; #pragma unroll
;             for (int db = 0; db < 2; ++db) {
;                 const v4i16_t a0 = __builtin_amdgcn_ds_read_tr16_b64_v4i16((LAS v4i16_t*)(vp + db * 64));
;                 const v4i16_t a1 = __builtin_amdgcn_ds_read_tr16_b64_v4i16((LAS v4i16_t*)(vp + db * 64 + 8 * VROW));
;                 const v4i16_t c0 = __builtin_amdgcn_ds_read_tr16_b64_v4i16((LAS v4i16_t*)(vp + db * 64 + 16 * VROW));
.LBB0_1110:
	s_nop 0
	s_waitcnt lgkmcnt(5)
	v_mfma_f32_32x32x16_bf16 v[48:63], v[202:205], v[74:77], v[32:47]
	s_waitcnt lgkmcnt(4)
	v_mfma_f32_32x32x16_bf16 v[48:63], v[206:209], v[78:81], v[48:63]
	s_waitcnt lgkmcnt(3)
	v_mfma_f32_32x32x16_bf16 v[48:63], v[210:213], v[82:85], v[48:63]
	s_waitcnt lgkmcnt(2)
	v_mfma_f32_32x32x16_bf16 v[48:63], v[214:217], v[90:93], v[48:63]
	s_waitcnt lgkmcnt(1)
	v_mfma_f32_32x32x16_bf16 v[48:63], v[218:221], v[94:97], v[48:63]
	s_waitcnt lgkmcnt(0)
	v_mfma_f32_32x32x16_bf16 v[48:63], v[222:225], v[98:101], v[48:63]
	v_add_u32_e32 v172, v119, v115
	ds_read_b64_tr_b16 v[156:157], v172 offset:19456
	ds_read_b64_tr_b16 v[158:159], v172 offset:20992
	ds_read_b64_tr_b16 v[160:161], v172 offset:22528
	ds_read_b64_tr_b16 v[162:163], v172 offset:24064
	ds_read_b64_tr_b16 v[164:165], v172 offset:19520
	ds_read_b64_tr_b16 v[166:167], v172 offset:21056
	ds_read_b64_tr_b16 v[168:169], v172 offset:22592
	ds_read_b64_tr_b16 v[170:171], v172 offset:24128
	s_nop 0
	s_add_i32 s30, s29, 0x7f
	s_cmp_le_i32 s30, s22
	s_cbranch_scc1 .LBB0_1112
	v_add_u32_e32 v120, s29, v105
	v_add_u32_e32 v121, 0x60, v120
	v_cmp_lt_i32_e32 vcc, v121, v139
	s_nop 4
	v_cndmask_b32_e32 v49, v239, v49, vcc
	v_cmp_le_i32_e32 vcc, v121, v139
	v_add_u32_e32 v121, 0x62, v120
	s_nop 0
	v_cndmask_b32_e32 v48, v239, v48, vcc
	v_cmp_le_i32_e32 vcc, v121, v139
	v_add_u32_e32 v121, 0x63, v120
	s_nop 0
	v_cndmask_b32_e32 v50, v239, v50, vcc
	v_cmp_le_i32_e32 vcc, v121, v139
	v_add_u32_e32 v121, 0x68, v120
	s_nop 0
	v_cndmask_b32_e32 v51, v239, v51, vcc
	v_cmp_le_i32_e32 vcc, v121, v139
	v_add_u32_e32 v121, 0x69, v120
	s_nop 0
	v_cndmask_b32_e32 v52, v239, v52, vcc
	v_cmp_le_i32_e32 vcc, v121, v139
	v_add_u32_e32 v121, 0x6a, v120
	s_nop 0
	v_cndmask_b32_e32 v53, v239, v53, vcc
	v_cmp_le_i32_e32 vcc, v121, v139
	v_add_u32_e32 v121, 0x6b, v120
	s_nop 0
	v_cndmask_b32_e32 v54, v239, v54, vcc
	v_cmp_le_i32_e32 vcc, v121, v139
	v_add_u32_e32 v121, 0x70, v120
	s_nop 0
	v_cndmask_b32_e32 v55, v239, v55, vcc
	v_cmp_le_i32_e32 vcc, v121, v139
	v_add_u32_e32 v121, 0x71, v120
	s_nop 0
	v_cndmask_b32_e32 v56, v239, v56, vcc
	v_cmp_le_i32_e32 vcc, v121, v139
	v_add_u32_e32 v121, 0x72, v120
	s_nop 0
	v_cndmask_b32_e32 v57, v239, v57, vcc
	v_cmp_le_i32_e32 vcc, v121, v139
	v_add_u32_e32 v121, 0x73, v120
	s_nop 0
	v_cndmask_b32_e32 v58, v239, v58, vcc
	v_cmp_le_i32_e32 vcc, v121, v139
	v_add_u32_e32 v121, 0x78, v120
	s_nop 0
	v_cndmask_b32_e32 v59, v239, v59, vcc
	v_cmp_le_i32_e32 vcc, v121, v139
	v_add_u32_e32 v121, 0x79, v120
	s_nop 0
	v_cndmask_b32_e32 v60, v239, v60, vcc
	v_cmp_le_i32_e32 vcc, v121, v139
	v_add_u32_e32 v121, 0x7a, v120
	v_add_u32_e32 v120, 0x7b, v120
	v_cndmask_b32_e32 v61, v239, v61, vcc
	v_cmp_le_i32_e32 vcc, v121, v139
	s_nop 1
	v_cndmask_b32_e32 v62, v239, v62, vcc
	v_cmp_le_i32_e32 vcc, v120, v139
	s_nop 1
	v_cndmask_b32_e32 v63, v239, v63, vcc

; __device__ __forceinline__ void xcd_barrier(const XcdBarrier& b) {
;     asm volatile("s_waitcnt vmcnt(0)" ::: "memory");
;     __syncthreads();
;     if (threadIdx.x == 0) {
;         unsigned* bar = b.bar;
;         __builtin_amdgcn_s_waitcnt(0);
;         unsigned nloc = b.st[0], nx = b.st[1];
;         if (nloc == 0u) { xcd_barrier_complete(bar, b.x, nloc, nx); b.st[0] = nloc; b.st[1] = nx; }
.LBB0_1120:
	s_setprio 0
	s_load_dwordx2 s[4:5], s[58:59], 0xb8
	s_waitcnt lgkmcnt(0)
	s_getreg_b32 s2, hwreg(HW_REG_XCC_ID, 0, 4)
	s_waitcnt vmcnt(0)
	s_barrier
	s_and_saveexec_b64 s[0:1], s[62:63]
	s_xor_b64 s[0:1], exec, s[0:1]
	s_mov_b32 s53, 0x10000
	s_mov_b32 s60, 0x18000
	s_mov_b32 s80, 0x8000
	s_mov_b32 s81, 0x40000
	s_cbranch_execz .LBB0_1173
	v_readlane_b32 s6, v254, 31
	s_waitcnt vmcnt(0) expcnt(0) lgkmcnt(0)
	s_and_b32 s2, s2, 15
	v_mov_b32_e32 v0, s6
	ds_read_b32 v2, v0
	v_readlane_b32 s6, v254, 32
	s_waitcnt lgkmcnt(0)
	v_cmp_ne_u32_e32 vcc, 0, v2
	v_mov_b32_e32 v0, s6
	ds_read_b32 v0, v0
	s_cbranch_vccnz .LBB0_1136
	s_add_u32 s6, s4, 0x9780200
	s_addc_u32 s7, s5, 0
	s_add_u32 s8, s4, 0x9780400
	s_addc_u32 s9, s5, 0
	s_add_u32 s10, s4, 0x9780500
	s_addc_u32 s11, s5, 0
	s_add_u32 s12, s4, 0x9780600
	s_addc_u32 s13, s5, 0
	s_add_u32 s14, s4, 0x9780700
	s_addc_u32 s15, s5, 0
	s_add_u32 s18, s4, 0x9780800
	s_addc_u32 s19, s5, 0
	s_add_u32 s20, s4, 0x9780900
	s_addc_u32 s21, s5, 0
	s_add_u32 s22, s4, 0x9780a00
	s_addc_u32 s23, s5, 0
	s_add_u32 s24, s4, 0x9780b00
	s_addc_u32 s25, s5, 0
	s_add_u32 s26, s4, 0x9780c00
	s_addc_u32 s27, s5, 0
	s_add_u32 s28, s4, 0x9780d00
	s_addc_u32 s29, s5, 0
	s_add_u32 s30, s4, 0x9780e00
	s_addc_u32 s31, s5, 0
	s_add_u32 s34, s4, 0x9780f00
	s_addc_u32 s35, s5, 0
	s_add_u32 s36, s4, 0x9781000
	s_addc_u32 s37, s5, 0
	s_add_u32 s38, s4, 0x9781100
	s_addc_u32 s39, s5, 0
	s_add_u32 s40, s4, 0x9781200
	s_addc_u32 s41, s5, 0
	s_add_u32 s42, s4, 0x9781300
	s_addc_u32 s43, s5, 0
	s_mov_b32 s50, 1
	s_branch .LBB0_1124
